# K=2048 GEMM loops: six s_nop 0 at the end of each load part (before the vmcnt wait) - light pacing of the loading half
# speedup vs baseline: 1.0000x; 1.0000x over previous
;     __device__ bool next(int i, Unit& u) const { if (!so.next(i >> 1, u)) return false; u.kind = i & 1; return true; }
; #define PG8_STAGE(bufoff, gbase, voff) do { _Pragma("unroll") for (int _i = 0; _i < 2; ++_i) \
;         __builtin_amdgcn_global_load_lds((const unsigned*)((const char*)(gbase) + (voff)[_i]), (LAS unsigned*)(lds + (bufoff) + ldsw + _i * 8192), 16, 0, 0); } while (0)
; #define PG8_LDA(dst, b, h) do { _Pragma("unroll") for (int m = 0; m < 4; ++m) _Pragma("unroll") for (int k = 0; k < 2; ++k) dst[m][k] = *(const LAS bf16x8*)(lds + PG8_SA(b, h) + aoff + m * 2048 + k * 1024); } while (0)
; #define PG8_LDB(dst, b, h) do { _Pragma("unroll") for (int n = 0; n < 2; ++n) _Pragma("unroll") for (int k = 0; k < 2; ++k) dst[n][k] = *(const LAS bf16x8*)(lds + PG8_SB(b, h) + boff + n * 2048 + k * 1024); } while (0)
; #define PG8_WAIT_V(n) asm volatile("s_waitcnt vmcnt(" #n ")" ::: "memory")
; #define PG8_WAIT_L(n) asm volatile("s_waitcnt lgkmcnt(" #n ")" ::: "memory")
; #define PG8_BAR __builtin_amdgcn_s_barrier()
; #define PG8_SCHED __builtin_amdgcn_sched_barrier(0)
; template <class Epi, class Sched, bool ALIGN_EPI = true, bool SP2 = true>
; __device__ __forceinline__ void gemm_phase(LAS unsigned char* lds, const Gemm g, const Sched& S, const Epi& E) {
;     ...
;         const bool has_next = S.next(ui + 1, nxt);
;         const char* nA = has_next ? (const char*)(nxt.kind ? g.A1 : g.A0) + (size_t)nxt.pm * tstep : cA; const char* nB = has_next ? (const char*)(nxt.kind ? g.B1 : g.B0) + (size_t)nxt.pn * tstep : cB;
;         for (int t = 0; t < nt; t += 2) {
;             const bool last = (t == nt - 2);
;             const char* a1 = cA + (size_t)(t + 1) * kstep;
;             const char* a2 = last ? nA : cA + (size_t)(t + 2) * kstep; const char* b2 = last ? nB : cB + (size_t)(t + 2) * kstep;
;             const char* a3 = a2 + kstep; const char* b3 = b2 + kstep;
;             if constexpr (SP2) {
;             PG8_LDB(B0, 0, 0); PG8_LDB(B1, 0, 1); PG8_SCHED; PG8_LDA(At, 0, 0); PG8_STAGE(PG8_SA(1, 1), a1 + hstep, voffA);
;             PG8_WAIT_V(8); PG8_WAIT_L(0); PG8_BAR; PG8_MMA(0, 0, At, B0); PG8_MMA(0, 1, At, B1); PG8_BAR; PG8_SCHED;
;             PG8_LDA(At, 0, 1); PG8_STAGE(PG8_SB(0, 0), b2, voffB); PG8_STAGE(PG8_SB(0, 1), b2 + hstep, voffB); PG8_STAGE(PG8_SA(0, 0), a2, voffA);
.LBB0_93:
	s_ashr_i32 s17, s16, 31
	s_lshl_b64 s[18:19], s[16:17], 20
	s_add_u32 s18, s88, s18
	s_addc_u32 s19, s89, s19
	s_and_b64 s[20:21], s[0:1], exec
	s_cselect_b32 s17, s19, s7
	s_cselect_b32 s56, s18, s6
	s_ashr_i32 s15, s14, 31
	s_lshl_b64 s[20:21], s[14:15], 20
	v_readlane_b32 s15, v255, 28
	s_add_u32 s20, s15, s20
	v_readlane_b32 s15, v255, 29
	s_addc_u32 s21, s15, s21
	s_and_b64 s[22:23], s[0:1], exec
	s_cselect_b32 s15, s21, s9
	s_cselect_b32 s57, s20, s8
	s_add_u32 s6, s6, 0x80080
	s_addc_u32 s7, s7, 0
	s_add_u32 s70, s8, 0x100
	s_addc_u32 s71, s9, 0
	s_mov_b32 s72, -2
	s_add_u32 s8, s6, 0xfff80080
	s_addc_u32 s9, s7, -1
	s_add_i32 s58, 0, 0x10000
	s_cmp_eq_u32 s72, 28
	s_cselect_b32 s23, s17, s9
	s_cselect_b32 s22, s56, s8
	v_add_u32_e32 v148, s58, v153
	s_cselect_b32 s9, s15, s71
	s_cselect_b32 s8, s57, s70
	s_add_i32 s73, 0, 0x14000
	ds_read_b128 v[140:143], v148
	ds_read_b128 v[144:147], v148 offset:1024
	ds_read_b128 v[160:163], v148 offset:2048
	ds_read_b128 v[164:167], v148 offset:3072
	ds_read_b128 v[168:171], v148 offset:16384
	ds_read_b128 v[172:175], v148 offset:17408
	ds_read_b128 v[176:179], v148 offset:18432
	ds_read_b128 v[194:197], v148 offset:19456
	s_add_i32 m0, s25, 0xc000
	ds_read_b128 v[198:201], v159
	ds_read_b128 v[202:205], v159 offset:1024
	ds_read_b128 v[206:209], v159 offset:2048
	ds_read_b128 v[210:213], v159 offset:3072
	ds_read_b128 v[234:237], v159 offset:4096
	ds_read_b128 v[238:241], v159 offset:5120
	ds_read_b128 v[242:245], v159 offset:6144
	ds_read_b128 v[246:249], v159 offset:7168
	global_load_lds_dwordx4 v136, s[6:7]
	s_add_i32 m0, s25, 0xe000
	s_nop 0
	global_load_lds_dwordx4 v138, s[6:7]
	s_nop 0
	s_nop 0
	s_nop 0
	s_nop 0
	s_nop 0
	s_nop 0
	s_waitcnt vmcnt(8)
	s_waitcnt lgkmcnt(0)
	s_barrier
	s_setprio 1
	s_waitcnt lgkmcnt(0)
	v_mfma_f32_16x16x32_bf16 v[126:129], v[140:143], v[198:201], 0
	v_mfma_f32_16x16x32_bf16 v[118:121], v[160:163], v[198:201], 0
	v_mfma_f32_16x16x32_bf16 v[110:113], v[140:143], v[206:209], 0
	v_mfma_f32_16x16x32_bf16 v[102:105], v[160:163], v[206:209], 0
	v_mfma_f32_16x16x32_bf16 v[94:97], v[140:143], v[234:237], 0
	v_mfma_f32_16x16x32_bf16 v[86:89], v[160:163], v[234:237], 0
	v_mfma_f32_16x16x32_bf16 v[78:81], v[140:143], v[242:245], 0
	v_mfma_f32_16x16x32_bf16 v[70:73], v[160:163], v[242:245], 0
	v_mfma_f32_16x16x32_bf16 v[126:129], v[144:147], v[202:205], v[126:129]
	v_mfma_f32_16x16x32_bf16 v[118:121], v[164:167], v[202:205], v[118:121]
	v_mfma_f32_16x16x32_bf16 v[110:113], v[144:147], v[210:213], v[110:113]
	v_mfma_f32_16x16x32_bf16 v[102:105], v[164:167], v[210:213], v[102:105]
	v_mfma_f32_16x16x32_bf16 v[94:97], v[144:147], v[238:241], v[94:97]
	v_mfma_f32_16x16x32_bf16 v[86:89], v[164:167], v[238:241], v[86:89]
	v_mfma_f32_16x16x32_bf16 v[78:81], v[144:147], v[246:249], v[78:81]
	v_mfma_f32_16x16x32_bf16 v[70:73], v[164:167], v[246:249], v[70:73]
	s_setprio 0
	s_setprio 1
	v_mfma_f32_16x16x32_bf16 v[122:125], v[168:171], v[198:201], 0
	v_mfma_f32_16x16x32_bf16 v[114:117], v[176:179], v[198:201], 0
	v_mfma_f32_16x16x32_bf16 v[106:109], v[168:171], v[206:209], 0
	v_mfma_f32_16x16x32_bf16 v[98:101], v[176:179], v[206:209], 0
	v_mfma_f32_16x16x32_bf16 v[90:93], v[168:171], v[234:237], 0
	v_mfma_f32_16x16x32_bf16 v[82:85], v[176:179], v[234:237], 0
	v_mfma_f32_16x16x32_bf16 v[74:77], v[168:171], v[242:245], 0
	v_mfma_f32_16x16x32_bf16 v[66:69], v[176:179], v[242:245], 0
	v_mfma_f32_16x16x32_bf16 v[122:125], v[172:175], v[202:205], v[122:125]
	v_mfma_f32_16x16x32_bf16 v[114:117], v[194:197], v[202:205], v[114:117]
	v_mfma_f32_16x16x32_bf16 v[106:109], v[172:175], v[210:213], v[106:109]
	v_mfma_f32_16x16x32_bf16 v[98:101], v[194:197], v[210:213], v[98:101]
	v_mfma_f32_16x16x32_bf16 v[90:93], v[172:175], v[238:241], v[90:93]
	v_mfma_f32_16x16x32_bf16 v[82:85], v[194:197], v[238:241], v[82:85]
	v_mfma_f32_16x16x32_bf16 v[74:77], v[172:175], v[246:249], v[74:77]
	v_mfma_f32_16x16x32_bf16 v[66:69], v[194:197], v[246:249], v[66:69]
	s_setprio 0
	s_barrier
	s_add_i32 s58, s58, s24
	s_mov_b32 m0, s58
	ds_read_b128 v[198:201], v159 offset:16384
	ds_read_b128 v[202:205], v159 offset:17408
	ds_read_b128 v[206:209], v159 offset:18432
	ds_read_b128 v[210:213], v159 offset:19456
	ds_read_b128 v[234:237], v159 offset:20480
	ds_read_b128 v[238:241], v159 offset:21504
	ds_read_b128 v[242:245], v159 offset:22528
	ds_read_b128 v[246:249], v159 offset:23552
	global_load_lds_dwordx4 v0, s[8:9]
	s_add_i32 m0, s58, 0x2000
	s_add_u32 s58, s8, 0x80000
	s_addc_u32 s59, s9, 0
	s_add_i32 s73, s73, s24
	global_load_lds_dwordx4 v130, s[8:9]
	s_mov_b32 m0, s73
	s_nop 0
	global_load_lds_dwordx4 v0, s[58:59]
	s_add_i32 m0, s73, 0x2000
	s_nop 0
	global_load_lds_dwordx4 v130, s[58:59]
	s_mov_b32 m0, s25
	s_nop 0
	global_load_lds_dwordx4 v134, s[22:23]
	s_mov_b32 m0, s26
	s_nop 0
	global_load_lds_dwordx4 v132, s[22:23]
	s_nop 0
	s_nop 0
	s_nop 0
	s_nop 0
	s_nop 0
	s_nop 0
	s_waitcnt vmcnt(8)
	s_waitcnt lgkmcnt(0)
	s_barrier
; #define PG8_STAGE(bufoff, gbase, voff) do { _Pragma("unroll") for (int _i = 0; _i < 2; ++_i) \
;         __builtin_amdgcn_global_load_lds((const unsigned*)((const char*)(gbase) + (voff)[_i]), (LAS unsigned*)(lds + (bufoff) + ldsw + _i * 8192), 16, 0, 0); } while (0)
; #define PG8_LDA(dst, b, h) do { _Pragma("unroll") for (int m = 0; m < 4; ++m) _Pragma("unroll") for (int k = 0; k < 2; ++k) dst[m][k] = *(const LAS bf16x8*)(lds + PG8_SA(b, h) + aoff + m * 2048 + k * 1024); } while (0)
; #define PG8_LDB(dst, b, h) do { _Pragma("unroll") for (int n = 0; n < 2; ++n) _Pragma("unroll") for (int k = 0; k < 2; ++k) dst[n][k] = *(const LAS bf16x8*)(lds + PG8_SB(b, h) + boff + n * 2048 + k * 1024); } while (0)
; #define PG8_MMA(ai, bj, At, Bt) do { __builtin_amdgcn_s_setprio(1); _Pragma("unroll") for (int m = 0; m < 4; ++m) _Pragma("unroll") for (int n = 0; n < 2; ++n) _Pragma("unroll") for (int k = 0; k < 2; ++k) \
;         acc[ai][bj][m][n] = __builtin_amdgcn_mfma_f32_16x16x32_bf16(Bt[n][k], At[m][k], acc[ai][bj][m][n], 0, 0, 0); __builtin_amdgcn_s_setprio(0); } while (0)
; #define PG8_WAIT_V(n) asm volatile("s_waitcnt vmcnt(" #n ")" ::: "memory")
; #define PG8_WAIT_L(n) asm volatile("s_waitcnt lgkmcnt(" #n ")" ::: "memory")
; #define PG8_BAR __builtin_amdgcn_s_barrier()
; #define PG8_SCHED __builtin_amdgcn_sched_barrier(0)
; template <class Epi, class Sched, bool ALIGN_EPI = true, bool SP2 = true>
; __device__ __forceinline__ void gemm_phase(LAS unsigned char* lds, const Gemm g, const Sched& S, const Epi& E) {
;     ...
;             PG8_WAIT_V(8); PG8_WAIT_L(0); PG8_BAR; PG8_MMA(1, 0, At, B0); PG8_MMA(1, 1, At, B1); PG8_BAR; PG8_SCHED;
;             PG8_LDB(B0, 1, 0); PG8_LDB(B1, 1, 1); PG8_SCHED; PG8_LDA(At, 1, 0); PG8_STAGE(PG8_SA(0, 1), a2 + hstep, voffA);
;             PG8_WAIT_V(8); PG8_WAIT_L(0); PG8_BAR; PG8_MMA(0, 0, At, B0); PG8_MMA(0, 1, At, B1); PG8_BAR; PG8_SCHED;
	s_setprio 1
	s_waitcnt lgkmcnt(0)
	v_mfma_f32_16x16x32_bf16 v[62:65], v[140:143], v[198:201], 0
	v_mfma_f32_16x16x32_bf16 v[54:57], v[160:163], v[198:201], 0
	v_mfma_f32_16x16x32_bf16 v[46:49], v[140:143], v[206:209], 0
	v_mfma_f32_16x16x32_bf16 v[38:41], v[160:163], v[206:209], 0
	v_mfma_f32_16x16x32_bf16 v[30:33], v[140:143], v[234:237], 0
	v_mfma_f32_16x16x32_bf16 v[22:25], v[160:163], v[234:237], 0
	v_mfma_f32_16x16x32_bf16 v[14:17], v[140:143], v[242:245], 0
	v_mfma_f32_16x16x32_bf16 v[6:9], v[160:163], v[242:245], 0
	v_mfma_f32_16x16x32_bf16 v[62:65], v[144:147], v[202:205], v[62:65]
	v_mfma_f32_16x16x32_bf16 v[54:57], v[164:167], v[202:205], v[54:57]
	v_mfma_f32_16x16x32_bf16 v[46:49], v[144:147], v[210:213], v[46:49]
	v_mfma_f32_16x16x32_bf16 v[38:41], v[164:167], v[210:213], v[38:41]
	v_mfma_f32_16x16x32_bf16 v[30:33], v[144:147], v[238:241], v[30:33]
	v_mfma_f32_16x16x32_bf16 v[22:25], v[164:167], v[238:241], v[22:25]
	v_mfma_f32_16x16x32_bf16 v[14:17], v[144:147], v[246:249], v[14:17]
	v_mfma_f32_16x16x32_bf16 v[6:9], v[164:167], v[246:249], v[6:9]
	s_setprio 0
	s_setprio 1
	v_mfma_f32_16x16x32_bf16 v[58:61], v[168:171], v[198:201], 0
	v_mfma_f32_16x16x32_bf16 v[50:53], v[176:179], v[198:201], 0
	v_mfma_f32_16x16x32_bf16 v[42:45], v[168:171], v[206:209], 0
	v_mfma_f32_16x16x32_bf16 v[34:37], v[176:179], v[206:209], 0
	v_mfma_f32_16x16x32_bf16 v[26:29], v[168:171], v[234:237], 0
	v_mfma_f32_16x16x32_bf16 v[18:21], v[176:179], v[234:237], 0
	v_mfma_f32_16x16x32_bf16 v[10:13], v[168:171], v[242:245], 0
	v_mfma_f32_16x16x32_bf16 v[2:5], v[176:179], v[242:245], 0
	v_mfma_f32_16x16x32_bf16 v[58:61], v[172:175], v[202:205], v[58:61]
	v_mfma_f32_16x16x32_bf16 v[50:53], v[194:197], v[202:205], v[50:53]
	v_mfma_f32_16x16x32_bf16 v[42:45], v[172:175], v[210:213], v[42:45]
	v_mfma_f32_16x16x32_bf16 v[34:37], v[194:197], v[210:213], v[34:37]
	v_mfma_f32_16x16x32_bf16 v[26:29], v[172:175], v[238:241], v[26:29]
	v_mfma_f32_16x16x32_bf16 v[18:21], v[194:197], v[238:241], v[18:21]
	v_mfma_f32_16x16x32_bf16 v[10:13], v[172:175], v[246:249], v[10:13]
	v_mfma_f32_16x16x32_bf16 v[2:5], v[194:197], v[246:249], v[2:5]
	s_setprio 0
	s_barrier
	s_add_i32 s58, 0, 0x18000
	v_add_u32_e32 v150, s58, v153
	s_add_i32 s59, 0, 0x1c000
	ds_read_b128 v[140:143], v150
	ds_read_b128 v[144:147], v150 offset:1024
	ds_read_b128 v[160:163], v150 offset:2048
	ds_read_b128 v[164:167], v150 offset:3072
	ds_read_b128 v[168:171], v150 offset:16384
	ds_read_b128 v[172:175], v150 offset:17408
	ds_read_b128 v[176:179], v150 offset:18432
	ds_read_b128 v[194:197], v150 offset:19456
	s_add_u32 s22, s22, 0x80000
	s_addc_u32 s23, s23, 0
	s_mov_b32 m0, s27
	ds_read_b128 v[198:201], v159 offset:32768
	ds_read_b128 v[202:205], v159 offset:33792
	ds_read_b128 v[206:209], v159 offset:34816
	ds_read_b128 v[210:213], v159 offset:35840
	ds_read_b128 v[234:237], v159 offset:36864
	ds_read_b128 v[238:241], v159 offset:37888
	ds_read_b128 v[242:245], v159 offset:38912
	ds_read_b128 v[246:249], v159 offset:39936
	global_load_lds_dwordx4 v134, s[22:23]
	s_mov_b32 m0, s28
	s_nop 0
	global_load_lds_dwordx4 v132, s[22:23]
	s_nop 0
	s_nop 0
	s_nop 0
	s_nop 0
	s_nop 0
	s_nop 0
	s_waitcnt vmcnt(8)
	s_waitcnt lgkmcnt(0)
	s_barrier
	s_setprio 1
	s_waitcnt lgkmcnt(0)
	v_mfma_f32_16x16x32_bf16 v[126:129], v[140:143], v[198:201], v[126:129]
	v_mfma_f32_16x16x32_bf16 v[118:121], v[160:163], v[198:201], v[118:121]
	v_mfma_f32_16x16x32_bf16 v[110:113], v[140:143], v[206:209], v[110:113]
	v_mfma_f32_16x16x32_bf16 v[102:105], v[160:163], v[206:209], v[102:105]
	v_mfma_f32_16x16x32_bf16 v[94:97], v[140:143], v[234:237], v[94:97]
	v_mfma_f32_16x16x32_bf16 v[86:89], v[160:163], v[234:237], v[86:89]
	v_mfma_f32_16x16x32_bf16 v[78:81], v[140:143], v[242:245], v[78:81]
	v_mfma_f32_16x16x32_bf16 v[70:73], v[160:163], v[242:245], v[70:73]
	v_mfma_f32_16x16x32_bf16 v[126:129], v[144:147], v[202:205], v[126:129]
	v_mfma_f32_16x16x32_bf16 v[118:121], v[164:167], v[202:205], v[118:121]
	v_mfma_f32_16x16x32_bf16 v[110:113], v[144:147], v[210:213], v[110:113]
	v_mfma_f32_16x16x32_bf16 v[102:105], v[164:167], v[210:213], v[102:105]
	v_mfma_f32_16x16x32_bf16 v[94:97], v[144:147], v[238:241], v[94:97]
	v_mfma_f32_16x16x32_bf16 v[86:89], v[164:167], v[238:241], v[86:89]
	v_mfma_f32_16x16x32_bf16 v[78:81], v[144:147], v[246:249], v[78:81]
	v_mfma_f32_16x16x32_bf16 v[70:73], v[164:167], v[246:249], v[70:73]
	s_setprio 0
	s_setprio 1
	v_mfma_f32_16x16x32_bf16 v[122:125], v[168:171], v[198:201], v[122:125]
	v_mfma_f32_16x16x32_bf16 v[114:117], v[176:179], v[198:201], v[114:117]
	v_mfma_f32_16x16x32_bf16 v[106:109], v[168:171], v[206:209], v[106:109]
	v_mfma_f32_16x16x32_bf16 v[98:101], v[176:179], v[206:209], v[98:101]
	v_mfma_f32_16x16x32_bf16 v[90:93], v[168:171], v[234:237], v[90:93]
	v_mfma_f32_16x16x32_bf16 v[82:85], v[176:179], v[234:237], v[82:85]
	v_mfma_f32_16x16x32_bf16 v[74:77], v[168:171], v[242:245], v[74:77]
	v_mfma_f32_16x16x32_bf16 v[66:69], v[176:179], v[242:245], v[66:69]
	v_mfma_f32_16x16x32_bf16 v[122:125], v[172:175], v[202:205], v[122:125]
	v_mfma_f32_16x16x32_bf16 v[114:117], v[194:197], v[202:205], v[114:117]
	v_mfma_f32_16x16x32_bf16 v[106:109], v[172:175], v[210:213], v[106:109]
	v_mfma_f32_16x16x32_bf16 v[98:101], v[194:197], v[210:213], v[98:101]
	v_mfma_f32_16x16x32_bf16 v[90:93], v[172:175], v[238:241], v[90:93]
	v_mfma_f32_16x16x32_bf16 v[82:85], v[194:197], v[238:241], v[82:85]
	v_mfma_f32_16x16x32_bf16 v[74:77], v[172:175], v[246:249], v[74:77]
	v_mfma_f32_16x16x32_bf16 v[66:69], v[194:197], v[246:249], v[66:69]
	s_setprio 0
	s_barrier
; #define PG8_STAGE(bufoff, gbase, voff) do { _Pragma("unroll") for (int _i = 0; _i < 2; ++_i) \
;         __builtin_amdgcn_global_load_lds((const unsigned*)((const char*)(gbase) + (voff)[_i]), (LAS unsigned*)(lds + (bufoff) + ldsw + _i * 8192), 16, 0, 0); } while (0)
; #define PG8_LDA(dst, b, h) do { _Pragma("unroll") for (int m = 0; m < 4; ++m) _Pragma("unroll") for (int k = 0; k < 2; ++k) dst[m][k] = *(const LAS bf16x8*)(lds + PG8_SA(b, h) + aoff + m * 2048 + k * 1024); } while (0)
; #define PG8_LDB(dst, b, h) do { _Pragma("unroll") for (int n = 0; n < 2; ++n) _Pragma("unroll") for (int k = 0; k < 2; ++k) dst[n][k] = *(const LAS bf16x8*)(lds + PG8_SB(b, h) + boff + n * 2048 + k * 1024); } while (0)
; #define PG8_WAIT_V(n) asm volatile("s_waitcnt vmcnt(" #n ")" ::: "memory")
; #define PG8_BAR __builtin_amdgcn_s_barrier()
; template <class Epi, class Sched, bool ALIGN_EPI = true, bool SP2 = true>
; __device__ __forceinline__ void gemm_phase(LAS unsigned char* lds, const Gemm g, const Sched& S, const Epi& E) {
;     ...
;             const bool last = (t == nt - 2);
;             const char* a1 = cA + (size_t)(t + 1) * kstep;
;             const char* a2 = last ? nA : cA + (size_t)(t + 2) * kstep; const char* b2 = last ? nB : cB + (size_t)(t + 2) * kstep;
;             const char* a3 = a2 + kstep; const char* b3 = b2 + kstep;
;             if constexpr (SP2) {
;             PG8_LDB(B0, 0, 0); PG8_LDB(B1, 0, 1); PG8_SCHED; PG8_LDA(At, 0, 0); PG8_STAGE(PG8_SA(1, 1), a1 + hstep, voffA);
;             PG8_WAIT_V(8); PG8_WAIT_L(0); PG8_BAR; PG8_MMA(0, 0, At, B0); PG8_MMA(0, 1, At, B1); PG8_BAR; PG8_SCHED;
;             PG8_LDA(At, 0, 1); PG8_STAGE(PG8_SB(0, 0), b2, voffB); PG8_STAGE(PG8_SB(0, 1), b2 + hstep, voffB); PG8_STAGE(PG8_SA(0, 0), a2, voffA);
;             PG8_WAIT_V(8); PG8_WAIT_L(0); PG8_BAR; PG8_MMA(1, 0, At, B0); PG8_MMA(1, 1, At, B1); PG8_BAR; PG8_SCHED;
;             PG8_LDB(B0, 1, 0); PG8_LDB(B1, 1, 1); PG8_SCHED; PG8_LDA(At, 1, 0); PG8_STAGE(PG8_SA(0, 1), a2 + hstep, voffA);
;             PG8_WAIT_V(8); PG8_WAIT_L(0); PG8_BAR; PG8_MMA(0, 0, At, B0); PG8_MMA(0, 1, At, B1); PG8_BAR; PG8_SCHED;
;             PG8_LDA(At, 1, 1); PG8_STAGE(PG8_SB(1, 0), b3, voffB); PG8_STAGE(PG8_SB(1, 1), b3 + hstep, voffB); PG8_STAGE(PG8_SA(1, 0), a3, voffA);
;             PG8_WAIT_V(8); PG8_WAIT_L(0); PG8_BAR; PG8_MMA(1, 0, At, B0); PG8_MMA(1, 1, At, B1); PG8_BAR; PG8_SCHED;
	s_add_i32 s32, s58, s24
	s_add_u32 s8, s8, s92
	s_addc_u32 s9, s9, s93
	s_mov_b32 m0, s32
	ds_read_b128 v[198:201], v159 offset:49152
	ds_read_b128 v[202:205], v159 offset:50176
	ds_read_b128 v[206:209], v159 offset:51200
	ds_read_b128 v[210:213], v159 offset:52224
	ds_read_b128 v[234:237], v159 offset:53248
	ds_read_b128 v[238:241], v159 offset:54272
	ds_read_b128 v[242:245], v159 offset:55296
	ds_read_b128 v[246:249], v159 offset:56320
	global_load_lds_dwordx4 v0, s[8:9]
	s_add_i32 m0, s32, 0x2000
	s_add_i32 s32, s59, s24
	global_load_lds_dwordx4 v130, s[8:9]
	s_add_u32 s8, s8, 0x80000
	s_addc_u32 s9, s9, 0
	s_mov_b32 m0, s32
	s_nop 0
	global_load_lds_dwordx4 v0, s[8:9]
	s_add_i32 m0, s32, 0x2000
	s_nop 0
	global_load_lds_dwordx4 v130, s[8:9]
	s_add_u32 s22, s22, 0xfff80080
	s_addc_u32 s23, s23, -1
	s_mov_b32 m0, s29
	s_nop 0
	global_load_lds_dwordx4 v134, s[22:23]
	s_mov_b32 m0, s30
	s_nop 0
	global_load_lds_dwordx4 v132, s[22:23]
	s_nop 0
	s_nop 0
	s_nop 0
	s_nop 0
	s_nop 0
	s_nop 0
	s_waitcnt vmcnt(8)
	s_waitcnt lgkmcnt(0)
	s_barrier
	s_setprio 1
	s_waitcnt lgkmcnt(0)
	v_mfma_f32_16x16x32_bf16 v[62:65], v[140:143], v[198:201], v[62:65]
	v_mfma_f32_16x16x32_bf16 v[54:57], v[160:163], v[198:201], v[54:57]
	v_mfma_f32_16x16x32_bf16 v[46:49], v[140:143], v[206:209], v[46:49]
	v_mfma_f32_16x16x32_bf16 v[38:41], v[160:163], v[206:209], v[38:41]
	v_mfma_f32_16x16x32_bf16 v[30:33], v[140:143], v[234:237], v[30:33]
	v_mfma_f32_16x16x32_bf16 v[22:25], v[160:163], v[234:237], v[22:25]
	v_mfma_f32_16x16x32_bf16 v[14:17], v[140:143], v[242:245], v[14:17]
	v_mfma_f32_16x16x32_bf16 v[6:9], v[160:163], v[242:245], v[6:9]
	v_mfma_f32_16x16x32_bf16 v[62:65], v[144:147], v[202:205], v[62:65]
	v_mfma_f32_16x16x32_bf16 v[54:57], v[164:167], v[202:205], v[54:57]
	v_mfma_f32_16x16x32_bf16 v[46:49], v[144:147], v[210:213], v[46:49]
	v_mfma_f32_16x16x32_bf16 v[38:41], v[164:167], v[210:213], v[38:41]
	v_mfma_f32_16x16x32_bf16 v[30:33], v[144:147], v[238:241], v[30:33]
	v_mfma_f32_16x16x32_bf16 v[22:25], v[164:167], v[238:241], v[22:25]
	v_mfma_f32_16x16x32_bf16 v[14:17], v[144:147], v[246:249], v[14:17]
	v_mfma_f32_16x16x32_bf16 v[6:9], v[164:167], v[246:249], v[6:9]
	s_setprio 0
	s_setprio 1
	v_mfma_f32_16x16x32_bf16 v[58:61], v[168:171], v[198:201], v[58:61]
	v_mfma_f32_16x16x32_bf16 v[50:53], v[176:179], v[198:201], v[50:53]
	v_mfma_f32_16x16x32_bf16 v[42:45], v[168:171], v[206:209], v[42:45]
	v_mfma_f32_16x16x32_bf16 v[34:37], v[176:179], v[206:209], v[34:37]
	v_mfma_f32_16x16x32_bf16 v[26:29], v[168:171], v[234:237], v[26:29]
	v_mfma_f32_16x16x32_bf16 v[18:21], v[176:179], v[234:237], v[18:21]
	v_mfma_f32_16x16x32_bf16 v[10:13], v[168:171], v[242:245], v[10:13]
	v_mfma_f32_16x16x32_bf16 v[2:5], v[176:179], v[242:245], v[2:5]
	v_mfma_f32_16x16x32_bf16 v[58:61], v[172:175], v[202:205], v[58:61]
	v_mfma_f32_16x16x32_bf16 v[50:53], v[194:197], v[202:205], v[50:53]
	v_mfma_f32_16x16x32_bf16 v[42:45], v[172:175], v[210:213], v[42:45]
	v_mfma_f32_16x16x32_bf16 v[34:37], v[194:197], v[210:213], v[34:37]
	v_mfma_f32_16x16x32_bf16 v[26:29], v[172:175], v[238:241], v[26:29]
	v_mfma_f32_16x16x32_bf16 v[18:21], v[194:197], v[238:241], v[18:21]
	v_mfma_f32_16x16x32_bf16 v[10:13], v[172:175], v[246:249], v[10:13]
	v_mfma_f32_16x16x32_bf16 v[2:5], v[194:197], v[246:249], v[2:5]
	s_setprio 0
	s_barrier
	s_add_i32 s72, s72, 2
	s_add_u32 s6, s6, 0x100
	s_addc_u32 s7, s7, 0
	s_add_u32 s70, s70, 0x100
	s_addc_u32 s71, s71, 0
	s_cmp_gt_u32 s72, 29
.LBB0_94:
	s_add_u32 s8, s6, 0xfff80080
	s_addc_u32 s9, s7, -1
	s_add_i32 s58, 0, 0x10000
	s_cmp_eq_u32 s72, 28
	s_cselect_b32 s23, s17, s9
	s_cselect_b32 s22, s56, s8
	v_add_u32_e32 v148, s58, v153
	s_cselect_b32 s9, s15, s71
	s_cselect_b32 s8, s57, s70
	s_add_i32 s73, 0, 0x14000
	ds_read_b128 v[140:143], v148
	ds_read_b128 v[144:147], v148 offset:1024
	ds_read_b128 v[160:163], v148 offset:2048
	ds_read_b128 v[164:167], v148 offset:3072
	ds_read_b128 v[168:171], v148 offset:16384
	ds_read_b128 v[172:175], v148 offset:17408
	ds_read_b128 v[176:179], v148 offset:18432
	ds_read_b128 v[194:197], v148 offset:19456
	s_add_i32 m0, s25, 0xc000
	ds_read_b128 v[198:201], v159
	ds_read_b128 v[202:205], v159 offset:1024
	ds_read_b128 v[206:209], v159 offset:2048
	ds_read_b128 v[210:213], v159 offset:3072
	ds_read_b128 v[234:237], v159 offset:4096
	ds_read_b128 v[238:241], v159 offset:5120
	ds_read_b128 v[242:245], v159 offset:6144
	ds_read_b128 v[246:249], v159 offset:7168
	global_load_lds_dwordx4 v136, s[6:7]
	s_add_i32 m0, s25, 0xe000
	s_nop 0
	global_load_lds_dwordx4 v138, s[6:7]
	s_nop 0
	s_nop 0
	s_nop 0
	s_nop 0
	s_nop 0
	s_nop 0
	s_waitcnt vmcnt(8)
	s_waitcnt lgkmcnt(0)
	s_barrier
; #define PG8_STAGE(bufoff, gbase, voff) do { _Pragma("unroll") for (int _i = 0; _i < 2; ++_i) \
;         __builtin_amdgcn_global_load_lds((const unsigned*)((const char*)(gbase) + (voff)[_i]), (LAS unsigned*)(lds + (bufoff) + ldsw + _i * 8192), 16, 0, 0); } while (0)
; #define PG8_LDA(dst, b, h) do { _Pragma("unroll") for (int m = 0; m < 4; ++m) _Pragma("unroll") for (int k = 0; k < 2; ++k) dst[m][k] = *(const LAS bf16x8*)(lds + PG8_SA(b, h) + aoff + m * 2048 + k * 1024); } while (0)
; #define PG8_MMA(ai, bj, At, Bt) do { __builtin_amdgcn_s_setprio(1); _Pragma("unroll") for (int m = 0; m < 4; ++m) _Pragma("unroll") for (int n = 0; n < 2; ++n) _Pragma("unroll") for (int k = 0; k < 2; ++k) \
;         acc[ai][bj][m][n] = __builtin_amdgcn_mfma_f32_16x16x32_bf16(Bt[n][k], At[m][k], acc[ai][bj][m][n], 0, 0, 0); __builtin_amdgcn_s_setprio(0); } while (0)
; #define PG8_WAIT_V(n) asm volatile("s_waitcnt vmcnt(" #n ")" ::: "memory")
; #define PG8_WAIT_L(n) asm volatile("s_waitcnt lgkmcnt(" #n ")" ::: "memory")
; #define PG8_BAR __builtin_amdgcn_s_barrier()
; #define PG8_SCHED __builtin_amdgcn_sched_barrier(0)
; template <class Epi, class Sched, bool ALIGN_EPI = true, bool SP2 = true>
; __device__ __forceinline__ void gemm_phase(LAS unsigned char* lds, const Gemm g, const Sched& S, const Epi& E) {
;     ...
;             PG8_WAIT_V(8); PG8_WAIT_L(0); PG8_BAR; PG8_MMA(0, 0, At, B0); PG8_MMA(0, 1, At, B1); PG8_BAR; PG8_SCHED;
;             PG8_LDA(At, 0, 1); PG8_STAGE(PG8_SB(0, 0), b2, voffB); PG8_STAGE(PG8_SB(0, 1), b2 + hstep, voffB); PG8_STAGE(PG8_SA(0, 0), a2, voffA);
;             PG8_WAIT_V(8); PG8_WAIT_L(0); PG8_BAR; PG8_MMA(1, 0, At, B0); PG8_MMA(1, 1, At, B1); PG8_BAR; PG8_SCHED;
	s_setprio 1
	s_waitcnt lgkmcnt(0)
	v_mfma_f32_16x16x32_bf16 v[126:129], v[140:143], v[198:201], v[126:129]
	v_mfma_f32_16x16x32_bf16 v[118:121], v[160:163], v[198:201], v[118:121]
	v_mfma_f32_16x16x32_bf16 v[110:113], v[140:143], v[206:209], v[110:113]
	v_mfma_f32_16x16x32_bf16 v[102:105], v[160:163], v[206:209], v[102:105]
	v_mfma_f32_16x16x32_bf16 v[94:97], v[140:143], v[234:237], v[94:97]
	v_mfma_f32_16x16x32_bf16 v[86:89], v[160:163], v[234:237], v[86:89]
	v_mfma_f32_16x16x32_bf16 v[78:81], v[140:143], v[242:245], v[78:81]
	v_mfma_f32_16x16x32_bf16 v[70:73], v[160:163], v[242:245], v[70:73]
	v_mfma_f32_16x16x32_bf16 v[126:129], v[144:147], v[202:205], v[126:129]
	v_mfma_f32_16x16x32_bf16 v[118:121], v[164:167], v[202:205], v[118:121]
	v_mfma_f32_16x16x32_bf16 v[110:113], v[144:147], v[210:213], v[110:113]
	v_mfma_f32_16x16x32_bf16 v[102:105], v[164:167], v[210:213], v[102:105]
	v_mfma_f32_16x16x32_bf16 v[94:97], v[144:147], v[238:241], v[94:97]
	v_mfma_f32_16x16x32_bf16 v[86:89], v[164:167], v[238:241], v[86:89]
	v_mfma_f32_16x16x32_bf16 v[78:81], v[144:147], v[246:249], v[78:81]
	v_mfma_f32_16x16x32_bf16 v[70:73], v[164:167], v[246:249], v[70:73]
	s_setprio 0
	s_setprio 1
	v_mfma_f32_16x16x32_bf16 v[122:125], v[168:171], v[198:201], v[122:125]
	v_mfma_f32_16x16x32_bf16 v[114:117], v[176:179], v[198:201], v[114:117]
	v_mfma_f32_16x16x32_bf16 v[106:109], v[168:171], v[206:209], v[106:109]
	v_mfma_f32_16x16x32_bf16 v[98:101], v[176:179], v[206:209], v[98:101]
	v_mfma_f32_16x16x32_bf16 v[90:93], v[168:171], v[234:237], v[90:93]
	v_mfma_f32_16x16x32_bf16 v[82:85], v[176:179], v[234:237], v[82:85]
	v_mfma_f32_16x16x32_bf16 v[74:77], v[168:171], v[242:245], v[74:77]
	v_mfma_f32_16x16x32_bf16 v[66:69], v[176:179], v[242:245], v[66:69]
	v_mfma_f32_16x16x32_bf16 v[122:125], v[172:175], v[202:205], v[122:125]
	v_mfma_f32_16x16x32_bf16 v[114:117], v[194:197], v[202:205], v[114:117]
	v_mfma_f32_16x16x32_bf16 v[106:109], v[172:175], v[210:213], v[106:109]
	v_mfma_f32_16x16x32_bf16 v[98:101], v[194:197], v[210:213], v[98:101]
	v_mfma_f32_16x16x32_bf16 v[90:93], v[172:175], v[238:241], v[90:93]
	v_mfma_f32_16x16x32_bf16 v[82:85], v[194:197], v[238:241], v[82:85]
	v_mfma_f32_16x16x32_bf16 v[74:77], v[172:175], v[246:249], v[74:77]
	v_mfma_f32_16x16x32_bf16 v[66:69], v[194:197], v[246:249], v[66:69]
	s_setprio 0
	s_barrier
	s_add_i32 s58, s58, s24
	s_mov_b32 m0, s58
	ds_read_b128 v[198:201], v159 offset:16384
	ds_read_b128 v[202:205], v159 offset:17408
	ds_read_b128 v[206:209], v159 offset:18432
	ds_read_b128 v[210:213], v159 offset:19456
	ds_read_b128 v[234:237], v159 offset:20480
	ds_read_b128 v[238:241], v159 offset:21504
	ds_read_b128 v[242:245], v159 offset:22528
	ds_read_b128 v[246:249], v159 offset:23552
	global_load_lds_dwordx4 v0, s[8:9]
	s_add_i32 m0, s58, 0x2000
	s_add_u32 s58, s8, 0x80000
	s_addc_u32 s59, s9, 0
	s_add_i32 s73, s73, s24
	global_load_lds_dwordx4 v130, s[8:9]
	s_mov_b32 m0, s73
	s_nop 0
	global_load_lds_dwordx4 v0, s[58:59]
	s_add_i32 m0, s73, 0x2000
	s_nop 0
	global_load_lds_dwordx4 v130, s[58:59]
	s_mov_b32 m0, s25
	s_nop 0
	global_load_lds_dwordx4 v134, s[22:23]
	s_mov_b32 m0, s26
	s_nop 0
	global_load_lds_dwordx4 v132, s[22:23]
	s_nop 0
	s_nop 0
	s_nop 0
	s_nop 0
	s_nop 0
	s_nop 0
	s_waitcnt vmcnt(8)
	s_waitcnt lgkmcnt(0)
	s_barrier
	s_setprio 1
	s_waitcnt lgkmcnt(0)
	v_mfma_f32_16x16x32_bf16 v[62:65], v[140:143], v[198:201], v[62:65]
	v_mfma_f32_16x16x32_bf16 v[54:57], v[160:163], v[198:201], v[54:57]
	v_mfma_f32_16x16x32_bf16 v[46:49], v[140:143], v[206:209], v[46:49]
	v_mfma_f32_16x16x32_bf16 v[38:41], v[160:163], v[206:209], v[38:41]
	v_mfma_f32_16x16x32_bf16 v[30:33], v[140:143], v[234:237], v[30:33]
	v_mfma_f32_16x16x32_bf16 v[22:25], v[160:163], v[234:237], v[22:25]
	v_mfma_f32_16x16x32_bf16 v[14:17], v[140:143], v[242:245], v[14:17]
	v_mfma_f32_16x16x32_bf16 v[6:9], v[160:163], v[242:245], v[6:9]
	v_mfma_f32_16x16x32_bf16 v[62:65], v[144:147], v[202:205], v[62:65]
	v_mfma_f32_16x16x32_bf16 v[54:57], v[164:167], v[202:205], v[54:57]
	v_mfma_f32_16x16x32_bf16 v[46:49], v[144:147], v[210:213], v[46:49]
	v_mfma_f32_16x16x32_bf16 v[38:41], v[164:167], v[210:213], v[38:41]
	v_mfma_f32_16x16x32_bf16 v[30:33], v[144:147], v[238:241], v[30:33]
	v_mfma_f32_16x16x32_bf16 v[22:25], v[164:167], v[238:241], v[22:25]
	v_mfma_f32_16x16x32_bf16 v[14:17], v[144:147], v[246:249], v[14:17]
	v_mfma_f32_16x16x32_bf16 v[6:9], v[164:167], v[246:249], v[6:9]
	s_setprio 0
	s_setprio 1
	v_mfma_f32_16x16x32_bf16 v[58:61], v[168:171], v[198:201], v[58:61]
	v_mfma_f32_16x16x32_bf16 v[50:53], v[176:179], v[198:201], v[50:53]
	v_mfma_f32_16x16x32_bf16 v[42:45], v[168:171], v[206:209], v[42:45]
	v_mfma_f32_16x16x32_bf16 v[34:37], v[176:179], v[206:209], v[34:37]
	v_mfma_f32_16x16x32_bf16 v[26:29], v[168:171], v[234:237], v[26:29]
	v_mfma_f32_16x16x32_bf16 v[18:21], v[176:179], v[234:237], v[18:21]
	v_mfma_f32_16x16x32_bf16 v[10:13], v[168:171], v[242:245], v[10:13]
	v_mfma_f32_16x16x32_bf16 v[2:5], v[176:179], v[242:245], v[2:5]
	v_mfma_f32_16x16x32_bf16 v[58:61], v[172:175], v[202:205], v[58:61]
	v_mfma_f32_16x16x32_bf16 v[50:53], v[194:197], v[202:205], v[50:53]
	v_mfma_f32_16x16x32_bf16 v[42:45], v[172:175], v[210:213], v[42:45]
	v_mfma_f32_16x16x32_bf16 v[34:37], v[194:197], v[210:213], v[34:37]
	v_mfma_f32_16x16x32_bf16 v[26:29], v[172:175], v[238:241], v[26:29]
	v_mfma_f32_16x16x32_bf16 v[18:21], v[194:197], v[238:241], v[18:21]
	v_mfma_f32_16x16x32_bf16 v[10:13], v[172:175], v[246:249], v[10:13]
	v_mfma_f32_16x16x32_bf16 v[2:5], v[194:197], v[246:249], v[2:5]
	s_setprio 0
	s_barrier
; #define PG8_STAGE(bufoff, gbase, voff) do { _Pragma("unroll") for (int _i = 0; _i < 2; ++_i) \
;         __builtin_amdgcn_global_load_lds((const unsigned*)((const char*)(gbase) + (voff)[_i]), (LAS unsigned*)(lds + (bufoff) + ldsw + _i * 8192), 16, 0, 0); } while (0)
; #define PG8_LDA(dst, b, h) do { _Pragma("unroll") for (int m = 0; m < 4; ++m) _Pragma("unroll") for (int k = 0; k < 2; ++k) dst[m][k] = *(const LAS bf16x8*)(lds + PG8_SA(b, h) + aoff + m * 2048 + k * 1024); } while (0)
; #define PG8_LDB(dst, b, h) do { _Pragma("unroll") for (int n = 0; n < 2; ++n) _Pragma("unroll") for (int k = 0; k < 2; ++k) dst[n][k] = *(const LAS bf16x8*)(lds + PG8_SB(b, h) + boff + n * 2048 + k * 1024); } while (0)
; #define PG8_MMA(ai, bj, At, Bt) do { __builtin_amdgcn_s_setprio(1); _Pragma("unroll") for (int m = 0; m < 4; ++m) _Pragma("unroll") for (int n = 0; n < 2; ++n) _Pragma("unroll") for (int k = 0; k < 2; ++k) \
;         acc[ai][bj][m][n] = __builtin_amdgcn_mfma_f32_16x16x32_bf16(Bt[n][k], At[m][k], acc[ai][bj][m][n], 0, 0, 0); __builtin_amdgcn_s_setprio(0); } while (0)
; #define PG8_WAIT_V(n) asm volatile("s_waitcnt vmcnt(" #n ")" ::: "memory")
; #define PG8_WAIT_L(n) asm volatile("s_waitcnt lgkmcnt(" #n ")" ::: "memory")
; #define PG8_BAR __builtin_amdgcn_s_barrier()
; #define PG8_SCHED __builtin_amdgcn_sched_barrier(0)
; template <class Epi, class Sched, bool ALIGN_EPI = true, bool SP2 = true>
; __device__ __forceinline__ void gemm_phase(LAS unsigned char* lds, const Gemm g, const Sched& S, const Epi& E) {
;     ...
;             PG8_LDB(B0, 1, 0); PG8_LDB(B1, 1, 1); PG8_SCHED; PG8_LDA(At, 1, 0); PG8_STAGE(PG8_SA(0, 1), a2 + hstep, voffA);
;             PG8_WAIT_V(8); PG8_WAIT_L(0); PG8_BAR; PG8_MMA(0, 0, At, B0); PG8_MMA(0, 1, At, B1); PG8_BAR; PG8_SCHED;
;             PG8_LDA(At, 1, 1); PG8_STAGE(PG8_SB(1, 0), b3, voffB); PG8_STAGE(PG8_SB(1, 1), b3 + hstep, voffB); PG8_STAGE(PG8_SA(1, 0), a3, voffA);
;             PG8_WAIT_V(8); PG8_WAIT_L(0); PG8_BAR; PG8_MMA(1, 0, At, B0); PG8_MMA(1, 1, At, B1); PG8_BAR; PG8_SCHED;
;     ...
;         if constexpr (ALIGN_EPI) { if (wr == 0) PG8_BAR; }
	s_add_i32 s58, 0, 0x18000
	v_add_u32_e32 v150, s58, v153
	s_add_i32 s59, 0, 0x1c000
	ds_read_b128 v[140:143], v150
	ds_read_b128 v[144:147], v150 offset:1024
	ds_read_b128 v[160:163], v150 offset:2048
	ds_read_b128 v[164:167], v150 offset:3072
	ds_read_b128 v[168:171], v150 offset:16384
	ds_read_b128 v[172:175], v150 offset:17408
	ds_read_b128 v[176:179], v150 offset:18432
	ds_read_b128 v[194:197], v150 offset:19456
	s_add_u32 s22, s22, 0x80000
	s_addc_u32 s23, s23, 0
	s_mov_b32 m0, s27
	ds_read_b128 v[198:201], v159 offset:32768
	ds_read_b128 v[202:205], v159 offset:33792
	ds_read_b128 v[206:209], v159 offset:34816
	ds_read_b128 v[210:213], v159 offset:35840
	ds_read_b128 v[234:237], v159 offset:36864
	ds_read_b128 v[238:241], v159 offset:37888
	ds_read_b128 v[242:245], v159 offset:38912
	ds_read_b128 v[246:249], v159 offset:39936
	global_load_lds_dwordx4 v134, s[22:23]
	s_mov_b32 m0, s28
	s_nop 0
	global_load_lds_dwordx4 v132, s[22:23]
	s_nop 0
	s_nop 0
	s_nop 0
	s_nop 0
	s_nop 0
	s_nop 0
	s_waitcnt vmcnt(8)
	s_waitcnt lgkmcnt(0)
	s_barrier
	s_setprio 1
	s_waitcnt lgkmcnt(0)
	v_mfma_f32_16x16x32_bf16 v[126:129], v[140:143], v[198:201], v[126:129]
	v_mfma_f32_16x16x32_bf16 v[118:121], v[160:163], v[198:201], v[118:121]
	v_mfma_f32_16x16x32_bf16 v[110:113], v[140:143], v[206:209], v[110:113]
	v_mfma_f32_16x16x32_bf16 v[102:105], v[160:163], v[206:209], v[102:105]
	v_mfma_f32_16x16x32_bf16 v[94:97], v[140:143], v[234:237], v[94:97]
	v_mfma_f32_16x16x32_bf16 v[86:89], v[160:163], v[234:237], v[86:89]
	v_mfma_f32_16x16x32_bf16 v[78:81], v[140:143], v[242:245], v[78:81]
	v_mfma_f32_16x16x32_bf16 v[70:73], v[160:163], v[242:245], v[70:73]
	v_mfma_f32_16x16x32_bf16 v[126:129], v[144:147], v[202:205], v[126:129]
	v_mfma_f32_16x16x32_bf16 v[118:121], v[164:167], v[202:205], v[118:121]
	v_mfma_f32_16x16x32_bf16 v[110:113], v[144:147], v[210:213], v[110:113]
	v_mfma_f32_16x16x32_bf16 v[102:105], v[164:167], v[210:213], v[102:105]
	v_mfma_f32_16x16x32_bf16 v[94:97], v[144:147], v[238:241], v[94:97]
	v_mfma_f32_16x16x32_bf16 v[86:89], v[164:167], v[238:241], v[86:89]
	v_mfma_f32_16x16x32_bf16 v[78:81], v[144:147], v[246:249], v[78:81]
	v_mfma_f32_16x16x32_bf16 v[70:73], v[164:167], v[246:249], v[70:73]
	s_setprio 0
	s_setprio 1
	v_mfma_f32_16x16x32_bf16 v[122:125], v[168:171], v[198:201], v[122:125]
	v_mfma_f32_16x16x32_bf16 v[114:117], v[176:179], v[198:201], v[114:117]
	v_mfma_f32_16x16x32_bf16 v[106:109], v[168:171], v[206:209], v[106:109]
	v_mfma_f32_16x16x32_bf16 v[98:101], v[176:179], v[206:209], v[98:101]
	v_mfma_f32_16x16x32_bf16 v[90:93], v[168:171], v[234:237], v[90:93]
	v_mfma_f32_16x16x32_bf16 v[82:85], v[176:179], v[234:237], v[82:85]
	v_mfma_f32_16x16x32_bf16 v[74:77], v[168:171], v[242:245], v[74:77]
	v_mfma_f32_16x16x32_bf16 v[66:69], v[176:179], v[242:245], v[66:69]
	v_mfma_f32_16x16x32_bf16 v[122:125], v[172:175], v[202:205], v[122:125]
	v_mfma_f32_16x16x32_bf16 v[114:117], v[194:197], v[202:205], v[114:117]
	v_mfma_f32_16x16x32_bf16 v[106:109], v[172:175], v[210:213], v[106:109]
	v_mfma_f32_16x16x32_bf16 v[98:101], v[194:197], v[210:213], v[98:101]
	v_mfma_f32_16x16x32_bf16 v[90:93], v[172:175], v[238:241], v[90:93]
	v_mfma_f32_16x16x32_bf16 v[82:85], v[194:197], v[238:241], v[82:85]
	v_mfma_f32_16x16x32_bf16 v[74:77], v[172:175], v[246:249], v[74:77]
	v_mfma_f32_16x16x32_bf16 v[66:69], v[194:197], v[246:249], v[66:69]
	s_setprio 0
	s_barrier
	s_add_i32 s32, s58, s24
	s_add_u32 s8, s8, s92
	s_addc_u32 s9, s9, s93
	s_mov_b32 m0, s32
	ds_read_b128 v[198:201], v159 offset:49152
	ds_read_b128 v[202:205], v159 offset:50176
	ds_read_b128 v[206:209], v159 offset:51200
	ds_read_b128 v[210:213], v159 offset:52224
	ds_read_b128 v[234:237], v159 offset:53248
	ds_read_b128 v[238:241], v159 offset:54272
	ds_read_b128 v[242:245], v159 offset:55296
	ds_read_b128 v[246:249], v159 offset:56320
	global_load_lds_dwordx4 v0, s[8:9]
	s_add_i32 m0, s32, 0x2000
	s_add_i32 s32, s59, s24
	global_load_lds_dwordx4 v130, s[8:9]
	s_add_u32 s8, s8, 0x80000
	s_addc_u32 s9, s9, 0
	s_mov_b32 m0, s32
	s_nop 0
	global_load_lds_dwordx4 v0, s[8:9]
	s_add_i32 m0, s32, 0x2000
	s_nop 0
	global_load_lds_dwordx4 v130, s[8:9]
	s_add_u32 s22, s22, 0xfff80080
	s_addc_u32 s23, s23, -1
	s_mov_b32 m0, s29
	s_nop 0
	global_load_lds_dwordx4 v134, s[22:23]
	s_mov_b32 m0, s30
	s_nop 0
	global_load_lds_dwordx4 v132, s[22:23]
	s_nop 0
	s_nop 0
	s_nop 0
	s_nop 0
	s_nop 0
	s_nop 0
	s_waitcnt vmcnt(8)
	s_waitcnt lgkmcnt(0)
	s_barrier
	s_setprio 1
	s_waitcnt lgkmcnt(0)
	v_mfma_f32_16x16x32_bf16 v[62:65], v[140:143], v[198:201], v[62:65]
	v_mfma_f32_16x16x32_bf16 v[54:57], v[160:163], v[198:201], v[54:57]
	v_mfma_f32_16x16x32_bf16 v[46:49], v[140:143], v[206:209], v[46:49]
	v_mfma_f32_16x16x32_bf16 v[38:41], v[160:163], v[206:209], v[38:41]
	v_mfma_f32_16x16x32_bf16 v[30:33], v[140:143], v[234:237], v[30:33]
	v_mfma_f32_16x16x32_bf16 v[22:25], v[160:163], v[234:237], v[22:25]
	v_mfma_f32_16x16x32_bf16 v[14:17], v[140:143], v[242:245], v[14:17]
	v_mfma_f32_16x16x32_bf16 v[6:9], v[160:163], v[242:245], v[6:9]
	v_mfma_f32_16x16x32_bf16 v[62:65], v[144:147], v[202:205], v[62:65]
	v_mfma_f32_16x16x32_bf16 v[54:57], v[164:167], v[202:205], v[54:57]
	v_mfma_f32_16x16x32_bf16 v[46:49], v[144:147], v[210:213], v[46:49]
	v_mfma_f32_16x16x32_bf16 v[38:41], v[164:167], v[210:213], v[38:41]
	v_mfma_f32_16x16x32_bf16 v[30:33], v[144:147], v[238:241], v[30:33]
	v_mfma_f32_16x16x32_bf16 v[22:25], v[164:167], v[238:241], v[22:25]
	v_mfma_f32_16x16x32_bf16 v[14:17], v[144:147], v[246:249], v[14:17]
	v_mfma_f32_16x16x32_bf16 v[6:9], v[164:167], v[246:249], v[6:9]
	s_setprio 0
	s_setprio 1
	v_mfma_f32_16x16x32_bf16 v[58:61], v[168:171], v[198:201], v[58:61]
	v_mfma_f32_16x16x32_bf16 v[50:53], v[176:179], v[198:201], v[50:53]
	v_mfma_f32_16x16x32_bf16 v[42:45], v[168:171], v[206:209], v[42:45]
	v_mfma_f32_16x16x32_bf16 v[34:37], v[176:179], v[206:209], v[34:37]
	v_mfma_f32_16x16x32_bf16 v[26:29], v[168:171], v[234:237], v[26:29]
	v_mfma_f32_16x16x32_bf16 v[18:21], v[176:179], v[234:237], v[18:21]
	v_mfma_f32_16x16x32_bf16 v[10:13], v[168:171], v[242:245], v[10:13]
	v_mfma_f32_16x16x32_bf16 v[2:5], v[176:179], v[242:245], v[2:5]
	v_mfma_f32_16x16x32_bf16 v[58:61], v[172:175], v[202:205], v[58:61]
	v_mfma_f32_16x16x32_bf16 v[50:53], v[194:197], v[202:205], v[50:53]
	v_mfma_f32_16x16x32_bf16 v[42:45], v[172:175], v[210:213], v[42:45]
	v_mfma_f32_16x16x32_bf16 v[34:37], v[194:197], v[210:213], v[34:37]
	v_mfma_f32_16x16x32_bf16 v[26:29], v[172:175], v[238:241], v[26:29]
	v_mfma_f32_16x16x32_bf16 v[18:21], v[194:197], v[238:241], v[18:21]
	v_mfma_f32_16x16x32_bf16 v[10:13], v[172:175], v[246:249], v[10:13]
	v_mfma_f32_16x16x32_bf16 v[2:5], v[194:197], v[246:249], v[2:5]
	s_setprio 0
	s_barrier
	s_add_i32 s72, s72, 2
	s_add_u32 s6, s6, 0x100
	s_addc_u32 s7, s7, 0
	s_add_u32 s70, s70, 0x100
	s_addc_u32 s71, s71, 0
	s_cmp_gt_u32 s72, 29
	s_cbranch_scc0 .LBB0_94
	s_and_b64 vcc, exec, s[12:13]
	s_cbranch_vccz .LBB0_97
	s_barrier

;     __device__ bool next(int i, Unit& u) const { if (!so.next(i >> 1, u)) return false; u.kind = i & 1; return true; }
; #define PG8_STAGE(bufoff, gbase, voff) do { _Pragma("unroll") for (int _i = 0; _i < 2; ++_i) \
;         __builtin_amdgcn_global_load_lds((const unsigned*)((const char*)(gbase) + (voff)[_i]), (LAS unsigned*)(lds + (bufoff) + ldsw + _i * 8192), 16, 0, 0); } while (0)
; #define PG8_LDA(dst, b, h) do { _Pragma("unroll") for (int m = 0; m < 4; ++m) _Pragma("unroll") for (int k = 0; k < 2; ++k) dst[m][k] = *(const LAS bf16x8*)(lds + PG8_SA(b, h) + aoff + m * 2048 + k * 1024); } while (0)
; #define PG8_LDB(dst, b, h) do { _Pragma("unroll") for (int n = 0; n < 2; ++n) _Pragma("unroll") for (int k = 0; k < 2; ++k) dst[n][k] = *(const LAS bf16x8*)(lds + PG8_SB(b, h) + boff + n * 2048 + k * 1024); } while (0)
; #define PG8_WAIT_V(n) asm volatile("s_waitcnt vmcnt(" #n ")" ::: "memory")
; #define PG8_WAIT_L(n) asm volatile("s_waitcnt lgkmcnt(" #n ")" ::: "memory")
; #define PG8_BAR __builtin_amdgcn_s_barrier()
; #define PG8_SCHED __builtin_amdgcn_sched_barrier(0)
; template <class Epi, class Sched, bool ALIGN_EPI = true, bool SP2 = true>
; __device__ __forceinline__ void gemm_phase(LAS unsigned char* lds, const Gemm g, const Sched& S, const Epi& E) {
;     ...
;         const bool has_next = S.next(ui + 1, nxt);
;         const char* nA = has_next ? (const char*)(nxt.kind ? g.A1 : g.A0) + (size_t)nxt.pm * tstep : cA; const char* nB = has_next ? (const char*)(nxt.kind ? g.B1 : g.B0) + (size_t)nxt.pn * tstep : cB;
;         for (int t = 0; t < nt; t += 2) {
;             const bool last = (t == nt - 2);
;             const char* a1 = cA + (size_t)(t + 1) * kstep;
;             const char* a2 = last ? nA : cA + (size_t)(t + 2) * kstep; const char* b2 = last ? nB : cB + (size_t)(t + 2) * kstep;
;             const char* a3 = a2 + kstep; const char* b3 = b2 + kstep;
;             if constexpr (SP2) {
;             PG8_LDB(B0, 0, 0); PG8_LDB(B1, 0, 1); PG8_SCHED; PG8_LDA(At, 0, 0); PG8_STAGE(PG8_SA(1, 1), a1 + hstep, voffA);
;             PG8_WAIT_V(8); PG8_WAIT_L(0); PG8_BAR; PG8_MMA(0, 0, At, B0); PG8_MMA(0, 1, At, B1); PG8_BAR; PG8_SCHED;
;             PG8_LDA(At, 0, 1); PG8_STAGE(PG8_SB(0, 0), b2, voffB); PG8_STAGE(PG8_SB(0, 1), b2 + hstep, voffB); PG8_STAGE(PG8_SA(0, 0), a2, voffA);
.LBB0_305:
	s_ashr_i32 s9, s8, 31
	s_lshl_b64 s[12:13], s[8:9], 20
	s_add_u32 s12, s88, s12
	s_addc_u32 s13, s89, s13
	s_and_b64 s[14:15], s[10:11], exec
	s_cselect_b32 s9, s13, s17
	s_cselect_b32 s70, s12, s16
	s_ashr_i32 s7, s6, 31
	s_lshl_b64 s[14:15], s[6:7], 20
	s_add_u32 s14, s24, s14
	s_addc_u32 s15, s25, s15
	s_and_b64 s[22:23], s[10:11], exec
	s_cselect_b32 s7, s15, s21
	s_cselect_b32 s71, s14, s20
	s_add_u32 s16, s16, 0x80080
	s_addc_u32 s17, s17, 0
	s_add_u32 s72, s20, 0x100
	s_addc_u32 s73, s21, 0
	s_mov_b32 s74, -2
	s_add_u32 s20, s16, 0xfff80080
	s_addc_u32 s21, s17, -1
	s_add_i32 s58, 0, 0x10000
	s_cmp_eq_u32 s74, 28
	s_cselect_b32 s23, s9, s21
	s_cselect_b32 s22, s70, s20
	v_add_u32_e32 v144, s58, v147
	s_cselect_b32 s21, s7, s73
	s_cselect_b32 s20, s71, s72
	s_add_i32 s75, 0, 0x14000
	ds_read_b128 v[140:143], v144
	ds_read_b128 v[154:157], v144 offset:1024
	ds_read_b128 v[158:161], v144 offset:2048
	ds_read_b128 v[162:165], v144 offset:3072
	ds_read_b128 v[166:169], v144 offset:16384
	ds_read_b128 v[170:173], v144 offset:17408
	ds_read_b128 v[174:177], v144 offset:18432
	ds_read_b128 v[194:197], v144 offset:19456
	s_add_i32 m0, s27, 0xc000
	ds_read_b128 v[198:201], v153
	ds_read_b128 v[202:205], v153 offset:1024
	ds_read_b128 v[206:209], v153 offset:2048
	ds_read_b128 v[210:213], v153 offset:3072
	ds_read_b128 v[234:237], v153 offset:4096
	ds_read_b128 v[238:241], v153 offset:5120
	ds_read_b128 v[242:245], v153 offset:6144
	ds_read_b128 v[246:249], v153 offset:7168
	global_load_lds_dwordx4 v136, s[16:17]
	s_add_i32 m0, s27, 0xe000
	s_nop 0
	global_load_lds_dwordx4 v138, s[16:17]
	s_nop 0
	s_nop 0
	s_nop 0
	s_nop 0
	s_nop 0
	s_nop 0
	s_waitcnt vmcnt(8)
	s_waitcnt lgkmcnt(0)
	s_barrier
	s_setprio 1
	s_waitcnt lgkmcnt(0)
	v_mfma_f32_16x16x32_bf16 v[126:129], v[140:143], v[198:201], 0
	v_mfma_f32_16x16x32_bf16 v[122:125], v[158:161], v[198:201], 0
	v_mfma_f32_16x16x32_bf16 v[114:117], v[140:143], v[206:209], 0
	v_mfma_f32_16x16x32_bf16 v[106:109], v[158:161], v[206:209], 0
	v_mfma_f32_16x16x32_bf16 v[98:101], v[140:143], v[234:237], 0
	v_mfma_f32_16x16x32_bf16 v[90:93], v[158:161], v[234:237], 0
	v_mfma_f32_16x16x32_bf16 v[82:85], v[140:143], v[242:245], 0
	v_mfma_f32_16x16x32_bf16 v[74:77], v[158:161], v[242:245], 0
	v_mfma_f32_16x16x32_bf16 v[126:129], v[154:157], v[202:205], v[126:129]
	v_mfma_f32_16x16x32_bf16 v[122:125], v[162:165], v[202:205], v[122:125]
	v_mfma_f32_16x16x32_bf16 v[114:117], v[154:157], v[210:213], v[114:117]
	v_mfma_f32_16x16x32_bf16 v[106:109], v[162:165], v[210:213], v[106:109]
	v_mfma_f32_16x16x32_bf16 v[98:101], v[154:157], v[238:241], v[98:101]
	v_mfma_f32_16x16x32_bf16 v[90:93], v[162:165], v[238:241], v[90:93]
	v_mfma_f32_16x16x32_bf16 v[82:85], v[154:157], v[246:249], v[82:85]
	v_mfma_f32_16x16x32_bf16 v[74:77], v[162:165], v[246:249], v[74:77]
	s_setprio 0
	s_setprio 1
	v_mfma_f32_16x16x32_bf16 v[118:121], v[166:169], v[198:201], 0
	v_mfma_f32_16x16x32_bf16 v[110:113], v[174:177], v[198:201], 0
	v_mfma_f32_16x16x32_bf16 v[102:105], v[166:169], v[206:209], 0
	v_mfma_f32_16x16x32_bf16 v[94:97], v[174:177], v[206:209], 0
	v_mfma_f32_16x16x32_bf16 v[86:89], v[166:169], v[234:237], 0
	v_mfma_f32_16x16x32_bf16 v[78:81], v[174:177], v[234:237], 0
	v_mfma_f32_16x16x32_bf16 v[70:73], v[166:169], v[242:245], 0
	v_mfma_f32_16x16x32_bf16 v[66:69], v[174:177], v[242:245], 0
	v_mfma_f32_16x16x32_bf16 v[118:121], v[170:173], v[202:205], v[118:121]
	v_mfma_f32_16x16x32_bf16 v[110:113], v[194:197], v[202:205], v[110:113]
	v_mfma_f32_16x16x32_bf16 v[102:105], v[170:173], v[210:213], v[102:105]
	v_mfma_f32_16x16x32_bf16 v[94:97], v[194:197], v[210:213], v[94:97]
	v_mfma_f32_16x16x32_bf16 v[86:89], v[170:173], v[238:241], v[86:89]
	v_mfma_f32_16x16x32_bf16 v[78:81], v[194:197], v[238:241], v[78:81]
	v_mfma_f32_16x16x32_bf16 v[70:73], v[170:173], v[246:249], v[70:73]
	v_mfma_f32_16x16x32_bf16 v[66:69], v[194:197], v[246:249], v[66:69]
	s_setprio 0
	s_barrier
	s_add_i32 s58, s58, s26
	s_mov_b32 m0, s58
	ds_read_b128 v[198:201], v153 offset:16384
	ds_read_b128 v[202:205], v153 offset:17408
	ds_read_b128 v[206:209], v153 offset:18432
	ds_read_b128 v[210:213], v153 offset:19456
	ds_read_b128 v[234:237], v153 offset:20480
	ds_read_b128 v[238:241], v153 offset:21504
	ds_read_b128 v[242:245], v153 offset:22528
	ds_read_b128 v[246:249], v153 offset:23552
	global_load_lds_dwordx4 v0, s[20:21]
	s_add_i32 m0, s58, 0x2000
	s_add_u32 s58, s20, 0x80000
	s_addc_u32 s59, s21, 0
	s_add_i32 s75, s75, s26
	global_load_lds_dwordx4 v130, s[20:21]
	s_mov_b32 m0, s75
	s_nop 0
	global_load_lds_dwordx4 v0, s[58:59]
	s_add_i32 m0, s75, 0x2000
	s_nop 0
	global_load_lds_dwordx4 v130, s[58:59]
	s_mov_b32 m0, s27
	s_nop 0
	global_load_lds_dwordx4 v134, s[22:23]
	s_mov_b32 m0, s28
	s_nop 0
	global_load_lds_dwordx4 v132, s[22:23]
	s_nop 0
	s_nop 0
	s_nop 0
	s_nop 0
	s_nop 0
	s_nop 0
	s_waitcnt vmcnt(8)
	s_waitcnt lgkmcnt(0)
	s_barrier
; #define PG8_STAGE(bufoff, gbase, voff) do { _Pragma("unroll") for (int _i = 0; _i < 2; ++_i) \
;         __builtin_amdgcn_global_load_lds((const unsigned*)((const char*)(gbase) + (voff)[_i]), (LAS unsigned*)(lds + (bufoff) + ldsw + _i * 8192), 16, 0, 0); } while (0)
; #define PG8_LDA(dst, b, h) do { _Pragma("unroll") for (int m = 0; m < 4; ++m) _Pragma("unroll") for (int k = 0; k < 2; ++k) dst[m][k] = *(const LAS bf16x8*)(lds + PG8_SA(b, h) + aoff + m * 2048 + k * 1024); } while (0)
; #define PG8_LDB(dst, b, h) do { _Pragma("unroll") for (int n = 0; n < 2; ++n) _Pragma("unroll") for (int k = 0; k < 2; ++k) dst[n][k] = *(const LAS bf16x8*)(lds + PG8_SB(b, h) + boff + n * 2048 + k * 1024); } while (0)
; #define PG8_MMA(ai, bj, At, Bt) do { __builtin_amdgcn_s_setprio(1); _Pragma("unroll") for (int m = 0; m < 4; ++m) _Pragma("unroll") for (int n = 0; n < 2; ++n) _Pragma("unroll") for (int k = 0; k < 2; ++k) \
;         acc[ai][bj][m][n] = __builtin_amdgcn_mfma_f32_16x16x32_bf16(Bt[n][k], At[m][k], acc[ai][bj][m][n], 0, 0, 0); __builtin_amdgcn_s_setprio(0); } while (0)
; #define PG8_WAIT_V(n) asm volatile("s_waitcnt vmcnt(" #n ")" ::: "memory")
; #define PG8_WAIT_L(n) asm volatile("s_waitcnt lgkmcnt(" #n ")" ::: "memory")
; #define PG8_BAR __builtin_amdgcn_s_barrier()
; #define PG8_SCHED __builtin_amdgcn_sched_barrier(0)
; template <class Epi, class Sched, bool ALIGN_EPI = true, bool SP2 = true>
; __device__ __forceinline__ void gemm_phase(LAS unsigned char* lds, const Gemm g, const Sched& S, const Epi& E) {
;     ...
;             PG8_WAIT_V(8); PG8_WAIT_L(0); PG8_BAR; PG8_MMA(1, 0, At, B0); PG8_MMA(1, 1, At, B1); PG8_BAR; PG8_SCHED;
;             PG8_LDB(B0, 1, 0); PG8_LDB(B1, 1, 1); PG8_SCHED; PG8_LDA(At, 1, 0); PG8_STAGE(PG8_SA(0, 1), a2 + hstep, voffA);
;             PG8_WAIT_V(8); PG8_WAIT_L(0); PG8_BAR; PG8_MMA(0, 0, At, B0); PG8_MMA(0, 1, At, B1); PG8_BAR; PG8_SCHED;
	s_setprio 1
	s_waitcnt lgkmcnt(0)
	v_mfma_f32_16x16x32_bf16 v[62:65], v[140:143], v[198:201], 0
	v_mfma_f32_16x16x32_bf16 v[58:61], v[158:161], v[198:201], 0
	v_mfma_f32_16x16x32_bf16 v[50:53], v[140:143], v[206:209], 0
	v_mfma_f32_16x16x32_bf16 v[42:45], v[158:161], v[206:209], 0
	v_mfma_f32_16x16x32_bf16 v[34:37], v[140:143], v[234:237], 0
	v_mfma_f32_16x16x32_bf16 v[26:29], v[158:161], v[234:237], 0
	v_mfma_f32_16x16x32_bf16 v[18:21], v[140:143], v[242:245], 0
	v_mfma_f32_16x16x32_bf16 v[10:13], v[158:161], v[242:245], 0
	v_mfma_f32_16x16x32_bf16 v[62:65], v[154:157], v[202:205], v[62:65]
	v_mfma_f32_16x16x32_bf16 v[58:61], v[162:165], v[202:205], v[58:61]
	v_mfma_f32_16x16x32_bf16 v[50:53], v[154:157], v[210:213], v[50:53]
	v_mfma_f32_16x16x32_bf16 v[42:45], v[162:165], v[210:213], v[42:45]
	v_mfma_f32_16x16x32_bf16 v[34:37], v[154:157], v[238:241], v[34:37]
	v_mfma_f32_16x16x32_bf16 v[26:29], v[162:165], v[238:241], v[26:29]
	v_mfma_f32_16x16x32_bf16 v[18:21], v[154:157], v[246:249], v[18:21]
	v_mfma_f32_16x16x32_bf16 v[10:13], v[162:165], v[246:249], v[10:13]
	s_setprio 0
	s_setprio 1
	v_mfma_f32_16x16x32_bf16 v[54:57], v[166:169], v[198:201], 0
	v_mfma_f32_16x16x32_bf16 v[46:49], v[174:177], v[198:201], 0
	v_mfma_f32_16x16x32_bf16 v[38:41], v[166:169], v[206:209], 0
	v_mfma_f32_16x16x32_bf16 v[30:33], v[174:177], v[206:209], 0
	v_mfma_f32_16x16x32_bf16 v[22:25], v[166:169], v[234:237], 0
	v_mfma_f32_16x16x32_bf16 v[14:17], v[174:177], v[234:237], 0
	v_mfma_f32_16x16x32_bf16 v[6:9], v[166:169], v[242:245], 0
	v_mfma_f32_16x16x32_bf16 v[2:5], v[174:177], v[242:245], 0
	v_mfma_f32_16x16x32_bf16 v[54:57], v[170:173], v[202:205], v[54:57]
	v_mfma_f32_16x16x32_bf16 v[46:49], v[194:197], v[202:205], v[46:49]
	v_mfma_f32_16x16x32_bf16 v[38:41], v[170:173], v[210:213], v[38:41]
	v_mfma_f32_16x16x32_bf16 v[30:33], v[194:197], v[210:213], v[30:33]
	v_mfma_f32_16x16x32_bf16 v[22:25], v[170:173], v[238:241], v[22:25]
	v_mfma_f32_16x16x32_bf16 v[14:17], v[194:197], v[238:241], v[14:17]
	v_mfma_f32_16x16x32_bf16 v[6:9], v[170:173], v[246:249], v[6:9]
	v_mfma_f32_16x16x32_bf16 v[2:5], v[194:197], v[246:249], v[2:5]
	s_setprio 0
	s_barrier
	s_add_i32 s58, 0, 0x18000
	v_add_u32_e32 v144, s58, v147
	s_add_i32 s59, 0, 0x1c000
	ds_read_b128 v[140:143], v144
	ds_read_b128 v[154:157], v144 offset:1024
	ds_read_b128 v[158:161], v144 offset:2048
	ds_read_b128 v[162:165], v144 offset:3072
	ds_read_b128 v[166:169], v144 offset:16384
	ds_read_b128 v[170:173], v144 offset:17408
	ds_read_b128 v[174:177], v144 offset:18432
	ds_read_b128 v[194:197], v144 offset:19456
	s_add_u32 s22, s22, 0x80000
	s_addc_u32 s23, s23, 0
	s_mov_b32 m0, s29
	ds_read_b128 v[198:201], v153 offset:32768
	ds_read_b128 v[202:205], v153 offset:33792
	ds_read_b128 v[206:209], v153 offset:34816
	ds_read_b128 v[210:213], v153 offset:35840
	ds_read_b128 v[234:237], v153 offset:36864
	ds_read_b128 v[238:241], v153 offset:37888
	ds_read_b128 v[242:245], v153 offset:38912
	ds_read_b128 v[246:249], v153 offset:39936
	global_load_lds_dwordx4 v134, s[22:23]
	s_mov_b32 m0, s30
	s_nop 0
	global_load_lds_dwordx4 v132, s[22:23]
	s_nop 0
	s_nop 0
	s_nop 0
	s_nop 0
	s_nop 0
	s_nop 0
	s_waitcnt vmcnt(8)
	s_waitcnt lgkmcnt(0)
	s_barrier
	s_setprio 1
	s_waitcnt lgkmcnt(0)
	v_mfma_f32_16x16x32_bf16 v[126:129], v[140:143], v[198:201], v[126:129]
	v_mfma_f32_16x16x32_bf16 v[122:125], v[158:161], v[198:201], v[122:125]
	v_mfma_f32_16x16x32_bf16 v[114:117], v[140:143], v[206:209], v[114:117]
	v_mfma_f32_16x16x32_bf16 v[106:109], v[158:161], v[206:209], v[106:109]
	v_mfma_f32_16x16x32_bf16 v[98:101], v[140:143], v[234:237], v[98:101]
	v_mfma_f32_16x16x32_bf16 v[90:93], v[158:161], v[234:237], v[90:93]
	v_mfma_f32_16x16x32_bf16 v[82:85], v[140:143], v[242:245], v[82:85]
	v_mfma_f32_16x16x32_bf16 v[74:77], v[158:161], v[242:245], v[74:77]
	v_mfma_f32_16x16x32_bf16 v[126:129], v[154:157], v[202:205], v[126:129]
	v_mfma_f32_16x16x32_bf16 v[122:125], v[162:165], v[202:205], v[122:125]
	v_mfma_f32_16x16x32_bf16 v[114:117], v[154:157], v[210:213], v[114:117]
	v_mfma_f32_16x16x32_bf16 v[106:109], v[162:165], v[210:213], v[106:109]
	v_mfma_f32_16x16x32_bf16 v[98:101], v[154:157], v[238:241], v[98:101]
	v_mfma_f32_16x16x32_bf16 v[90:93], v[162:165], v[238:241], v[90:93]
	v_mfma_f32_16x16x32_bf16 v[82:85], v[154:157], v[246:249], v[82:85]
	v_mfma_f32_16x16x32_bf16 v[74:77], v[162:165], v[246:249], v[74:77]
	s_setprio 0
	s_setprio 1
	v_mfma_f32_16x16x32_bf16 v[118:121], v[166:169], v[198:201], v[118:121]
	v_mfma_f32_16x16x32_bf16 v[110:113], v[174:177], v[198:201], v[110:113]
	v_mfma_f32_16x16x32_bf16 v[102:105], v[166:169], v[206:209], v[102:105]
	v_mfma_f32_16x16x32_bf16 v[94:97], v[174:177], v[206:209], v[94:97]
	v_mfma_f32_16x16x32_bf16 v[86:89], v[166:169], v[234:237], v[86:89]
	v_mfma_f32_16x16x32_bf16 v[78:81], v[174:177], v[234:237], v[78:81]
	v_mfma_f32_16x16x32_bf16 v[70:73], v[166:169], v[242:245], v[70:73]
	v_mfma_f32_16x16x32_bf16 v[66:69], v[174:177], v[242:245], v[66:69]
	v_mfma_f32_16x16x32_bf16 v[118:121], v[170:173], v[202:205], v[118:121]
	v_mfma_f32_16x16x32_bf16 v[110:113], v[194:197], v[202:205], v[110:113]
	v_mfma_f32_16x16x32_bf16 v[102:105], v[170:173], v[210:213], v[102:105]
	v_mfma_f32_16x16x32_bf16 v[94:97], v[194:197], v[210:213], v[94:97]
	v_mfma_f32_16x16x32_bf16 v[86:89], v[170:173], v[238:241], v[86:89]
	v_mfma_f32_16x16x32_bf16 v[78:81], v[194:197], v[238:241], v[78:81]
	v_mfma_f32_16x16x32_bf16 v[70:73], v[170:173], v[246:249], v[70:73]
	v_mfma_f32_16x16x32_bf16 v[66:69], v[194:197], v[246:249], v[66:69]
	s_setprio 0
	s_barrier
; #define PG8_STAGE(bufoff, gbase, voff) do { _Pragma("unroll") for (int _i = 0; _i < 2; ++_i) \
;         __builtin_amdgcn_global_load_lds((const unsigned*)((const char*)(gbase) + (voff)[_i]), (LAS unsigned*)(lds + (bufoff) + ldsw + _i * 8192), 16, 0, 0); } while (0)
; #define PG8_LDA(dst, b, h) do { _Pragma("unroll") for (int m = 0; m < 4; ++m) _Pragma("unroll") for (int k = 0; k < 2; ++k) dst[m][k] = *(const LAS bf16x8*)(lds + PG8_SA(b, h) + aoff + m * 2048 + k * 1024); } while (0)
; #define PG8_LDB(dst, b, h) do { _Pragma("unroll") for (int n = 0; n < 2; ++n) _Pragma("unroll") for (int k = 0; k < 2; ++k) dst[n][k] = *(const LAS bf16x8*)(lds + PG8_SB(b, h) + boff + n * 2048 + k * 1024); } while (0)
; #define PG8_WAIT_V(n) asm volatile("s_waitcnt vmcnt(" #n ")" ::: "memory")
; #define PG8_BAR __builtin_amdgcn_s_barrier()
; template <class Epi, class Sched, bool ALIGN_EPI = true, bool SP2 = true>
; __device__ __forceinline__ void gemm_phase(LAS unsigned char* lds, const Gemm g, const Sched& S, const Epi& E) {
;     ...
;             const bool last = (t == nt - 2);
;             const char* a1 = cA + (size_t)(t + 1) * kstep;
;             const char* a2 = last ? nA : cA + (size_t)(t + 2) * kstep; const char* b2 = last ? nB : cB + (size_t)(t + 2) * kstep;
;             const char* a3 = a2 + kstep; const char* b3 = b2 + kstep;
;             if constexpr (SP2) {
;             PG8_LDB(B0, 0, 0); PG8_LDB(B1, 0, 1); PG8_SCHED; PG8_LDA(At, 0, 0); PG8_STAGE(PG8_SA(1, 1), a1 + hstep, voffA);
;             PG8_WAIT_V(8); PG8_WAIT_L(0); PG8_BAR; PG8_MMA(0, 0, At, B0); PG8_MMA(0, 1, At, B1); PG8_BAR; PG8_SCHED;
;             PG8_LDA(At, 0, 1); PG8_STAGE(PG8_SB(0, 0), b2, voffB); PG8_STAGE(PG8_SB(0, 1), b2 + hstep, voffB); PG8_STAGE(PG8_SA(0, 0), a2, voffA);
;             PG8_WAIT_V(8); PG8_WAIT_L(0); PG8_BAR; PG8_MMA(1, 0, At, B0); PG8_MMA(1, 1, At, B1); PG8_BAR; PG8_SCHED;
;             PG8_LDB(B0, 1, 0); PG8_LDB(B1, 1, 1); PG8_SCHED; PG8_LDA(At, 1, 0); PG8_STAGE(PG8_SA(0, 1), a2 + hstep, voffA);
;             PG8_WAIT_V(8); PG8_WAIT_L(0); PG8_BAR; PG8_MMA(0, 0, At, B0); PG8_MMA(0, 1, At, B1); PG8_BAR; PG8_SCHED;
;             PG8_LDA(At, 1, 1); PG8_STAGE(PG8_SB(1, 0), b3, voffB); PG8_STAGE(PG8_SB(1, 1), b3 + hstep, voffB); PG8_STAGE(PG8_SA(1, 0), a3, voffA);
;             PG8_WAIT_V(8); PG8_WAIT_L(0); PG8_BAR; PG8_MMA(1, 0, At, B0); PG8_MMA(1, 1, At, B1); PG8_BAR; PG8_SCHED;
	s_add_i32 s32, s58, s26
	s_add_u32 s20, s20, s92
	s_addc_u32 s21, s21, s93
	s_mov_b32 m0, s32
	ds_read_b128 v[198:201], v153 offset:49152
	ds_read_b128 v[202:205], v153 offset:50176
	ds_read_b128 v[206:209], v153 offset:51200
	ds_read_b128 v[210:213], v153 offset:52224
	ds_read_b128 v[234:237], v153 offset:53248
	ds_read_b128 v[238:241], v153 offset:54272
	ds_read_b128 v[242:245], v153 offset:55296
	ds_read_b128 v[246:249], v153 offset:56320
	global_load_lds_dwordx4 v0, s[20:21]
	s_add_i32 m0, s32, 0x2000
	s_add_i32 s32, s59, s26
	global_load_lds_dwordx4 v130, s[20:21]
	s_add_u32 s20, s20, 0x80000
	s_addc_u32 s21, s21, 0
	s_mov_b32 m0, s32
	s_nop 0
	global_load_lds_dwordx4 v0, s[20:21]
	s_add_i32 m0, s32, 0x2000
	s_nop 0
	global_load_lds_dwordx4 v130, s[20:21]
	s_add_u32 s22, s22, 0xfff80080
	s_addc_u32 s23, s23, -1
	s_mov_b32 m0, s31
	s_nop 0
	global_load_lds_dwordx4 v134, s[22:23]
	s_mov_b32 m0, s34
	s_nop 0
	global_load_lds_dwordx4 v132, s[22:23]
	s_nop 0
	s_nop 0
	s_nop 0
	s_nop 0
	s_nop 0
	s_nop 0
	s_waitcnt vmcnt(8)
	s_waitcnt lgkmcnt(0)
	s_barrier
	s_setprio 1
	s_waitcnt lgkmcnt(0)
	v_mfma_f32_16x16x32_bf16 v[62:65], v[140:143], v[198:201], v[62:65]
	v_mfma_f32_16x16x32_bf16 v[58:61], v[158:161], v[198:201], v[58:61]
	v_mfma_f32_16x16x32_bf16 v[50:53], v[140:143], v[206:209], v[50:53]
	v_mfma_f32_16x16x32_bf16 v[42:45], v[158:161], v[206:209], v[42:45]
	v_mfma_f32_16x16x32_bf16 v[34:37], v[140:143], v[234:237], v[34:37]
	v_mfma_f32_16x16x32_bf16 v[26:29], v[158:161], v[234:237], v[26:29]
	v_mfma_f32_16x16x32_bf16 v[18:21], v[140:143], v[242:245], v[18:21]
	v_mfma_f32_16x16x32_bf16 v[10:13], v[158:161], v[242:245], v[10:13]
	v_mfma_f32_16x16x32_bf16 v[62:65], v[154:157], v[202:205], v[62:65]
	v_mfma_f32_16x16x32_bf16 v[58:61], v[162:165], v[202:205], v[58:61]
	v_mfma_f32_16x16x32_bf16 v[50:53], v[154:157], v[210:213], v[50:53]
	v_mfma_f32_16x16x32_bf16 v[42:45], v[162:165], v[210:213], v[42:45]
	v_mfma_f32_16x16x32_bf16 v[34:37], v[154:157], v[238:241], v[34:37]
	v_mfma_f32_16x16x32_bf16 v[26:29], v[162:165], v[238:241], v[26:29]
	v_mfma_f32_16x16x32_bf16 v[18:21], v[154:157], v[246:249], v[18:21]
	v_mfma_f32_16x16x32_bf16 v[10:13], v[162:165], v[246:249], v[10:13]
	s_setprio 0
	s_setprio 1
	v_mfma_f32_16x16x32_bf16 v[54:57], v[166:169], v[198:201], v[54:57]
	v_mfma_f32_16x16x32_bf16 v[46:49], v[174:177], v[198:201], v[46:49]
	v_mfma_f32_16x16x32_bf16 v[38:41], v[166:169], v[206:209], v[38:41]
	v_mfma_f32_16x16x32_bf16 v[30:33], v[174:177], v[206:209], v[30:33]
	v_mfma_f32_16x16x32_bf16 v[22:25], v[166:169], v[234:237], v[22:25]
	v_mfma_f32_16x16x32_bf16 v[14:17], v[174:177], v[234:237], v[14:17]
	v_mfma_f32_16x16x32_bf16 v[6:9], v[166:169], v[242:245], v[6:9]
	v_mfma_f32_16x16x32_bf16 v[2:5], v[174:177], v[242:245], v[2:5]
	v_mfma_f32_16x16x32_bf16 v[54:57], v[170:173], v[202:205], v[54:57]
	v_mfma_f32_16x16x32_bf16 v[46:49], v[194:197], v[202:205], v[46:49]
	v_mfma_f32_16x16x32_bf16 v[38:41], v[170:173], v[210:213], v[38:41]
	v_mfma_f32_16x16x32_bf16 v[30:33], v[194:197], v[210:213], v[30:33]
	v_mfma_f32_16x16x32_bf16 v[22:25], v[170:173], v[238:241], v[22:25]
	v_mfma_f32_16x16x32_bf16 v[14:17], v[194:197], v[238:241], v[14:17]
	v_mfma_f32_16x16x32_bf16 v[6:9], v[170:173], v[246:249], v[6:9]
	v_mfma_f32_16x16x32_bf16 v[2:5], v[194:197], v[246:249], v[2:5]
	s_setprio 0
	s_barrier
	s_add_i32 s74, s74, 2
	s_add_u32 s16, s16, 0x100
	s_addc_u32 s17, s17, 0
	s_add_u32 s72, s72, 0x100
	s_addc_u32 s73, s73, 0
	s_cmp_gt_u32 s74, 29
.LBB0_306:
	s_add_u32 s20, s16, 0xfff80080
	s_addc_u32 s21, s17, -1
	s_add_i32 s58, 0, 0x10000
	s_cmp_eq_u32 s74, 28
	s_cselect_b32 s23, s9, s21
	s_cselect_b32 s22, s70, s20
	v_add_u32_e32 v144, s58, v147
	s_cselect_b32 s21, s7, s73
	s_cselect_b32 s20, s71, s72
	s_add_i32 s75, 0, 0x14000
	ds_read_b128 v[140:143], v144
	ds_read_b128 v[154:157], v144 offset:1024
	ds_read_b128 v[158:161], v144 offset:2048
	ds_read_b128 v[162:165], v144 offset:3072
	ds_read_b128 v[166:169], v144 offset:16384
	ds_read_b128 v[170:173], v144 offset:17408
	ds_read_b128 v[174:177], v144 offset:18432
	ds_read_b128 v[194:197], v144 offset:19456
	s_add_i32 m0, s27, 0xc000
	ds_read_b128 v[198:201], v153
	ds_read_b128 v[202:205], v153 offset:1024
	ds_read_b128 v[206:209], v153 offset:2048
	ds_read_b128 v[210:213], v153 offset:3072
	ds_read_b128 v[234:237], v153 offset:4096
	ds_read_b128 v[238:241], v153 offset:5120
	ds_read_b128 v[242:245], v153 offset:6144
	ds_read_b128 v[246:249], v153 offset:7168
	global_load_lds_dwordx4 v136, s[16:17]
	s_add_i32 m0, s27, 0xe000
	s_nop 0
	global_load_lds_dwordx4 v138, s[16:17]
	s_nop 0
	s_nop 0
	s_nop 0
	s_nop 0
	s_nop 0
	s_nop 0
	s_waitcnt vmcnt(8)
	s_waitcnt lgkmcnt(0)
	s_barrier
; #define PG8_STAGE(bufoff, gbase, voff) do { _Pragma("unroll") for (int _i = 0; _i < 2; ++_i) \
;         __builtin_amdgcn_global_load_lds((const unsigned*)((const char*)(gbase) + (voff)[_i]), (LAS unsigned*)(lds + (bufoff) + ldsw + _i * 8192), 16, 0, 0); } while (0)
; #define PG8_LDA(dst, b, h) do { _Pragma("unroll") for (int m = 0; m < 4; ++m) _Pragma("unroll") for (int k = 0; k < 2; ++k) dst[m][k] = *(const LAS bf16x8*)(lds + PG8_SA(b, h) + aoff + m * 2048 + k * 1024); } while (0)
; #define PG8_MMA(ai, bj, At, Bt) do { __builtin_amdgcn_s_setprio(1); _Pragma("unroll") for (int m = 0; m < 4; ++m) _Pragma("unroll") for (int n = 0; n < 2; ++n) _Pragma("unroll") for (int k = 0; k < 2; ++k) \
;         acc[ai][bj][m][n] = __builtin_amdgcn_mfma_f32_16x16x32_bf16(Bt[n][k], At[m][k], acc[ai][bj][m][n], 0, 0, 0); __builtin_amdgcn_s_setprio(0); } while (0)
; #define PG8_WAIT_V(n) asm volatile("s_waitcnt vmcnt(" #n ")" ::: "memory")
; #define PG8_WAIT_L(n) asm volatile("s_waitcnt lgkmcnt(" #n ")" ::: "memory")
; #define PG8_BAR __builtin_amdgcn_s_barrier()
; #define PG8_SCHED __builtin_amdgcn_sched_barrier(0)
; template <class Epi, class Sched, bool ALIGN_EPI = true, bool SP2 = true>
; __device__ __forceinline__ void gemm_phase(LAS unsigned char* lds, const Gemm g, const Sched& S, const Epi& E) {
;     ...
;             PG8_WAIT_V(8); PG8_WAIT_L(0); PG8_BAR; PG8_MMA(0, 0, At, B0); PG8_MMA(0, 1, At, B1); PG8_BAR; PG8_SCHED;
;             PG8_LDA(At, 0, 1); PG8_STAGE(PG8_SB(0, 0), b2, voffB); PG8_STAGE(PG8_SB(0, 1), b2 + hstep, voffB); PG8_STAGE(PG8_SA(0, 0), a2, voffA);
;             PG8_WAIT_V(8); PG8_WAIT_L(0); PG8_BAR; PG8_MMA(1, 0, At, B0); PG8_MMA(1, 1, At, B1); PG8_BAR; PG8_SCHED;
	s_setprio 1
	s_waitcnt lgkmcnt(0)
	v_mfma_f32_16x16x32_bf16 v[126:129], v[140:143], v[198:201], v[126:129]
	v_mfma_f32_16x16x32_bf16 v[122:125], v[158:161], v[198:201], v[122:125]
	v_mfma_f32_16x16x32_bf16 v[114:117], v[140:143], v[206:209], v[114:117]
	v_mfma_f32_16x16x32_bf16 v[106:109], v[158:161], v[206:209], v[106:109]
	v_mfma_f32_16x16x32_bf16 v[98:101], v[140:143], v[234:237], v[98:101]
	v_mfma_f32_16x16x32_bf16 v[90:93], v[158:161], v[234:237], v[90:93]
	v_mfma_f32_16x16x32_bf16 v[82:85], v[140:143], v[242:245], v[82:85]
	v_mfma_f32_16x16x32_bf16 v[74:77], v[158:161], v[242:245], v[74:77]
	v_mfma_f32_16x16x32_bf16 v[126:129], v[154:157], v[202:205], v[126:129]
	v_mfma_f32_16x16x32_bf16 v[122:125], v[162:165], v[202:205], v[122:125]
	v_mfma_f32_16x16x32_bf16 v[114:117], v[154:157], v[210:213], v[114:117]
	v_mfma_f32_16x16x32_bf16 v[106:109], v[162:165], v[210:213], v[106:109]
	v_mfma_f32_16x16x32_bf16 v[98:101], v[154:157], v[238:241], v[98:101]
	v_mfma_f32_16x16x32_bf16 v[90:93], v[162:165], v[238:241], v[90:93]
	v_mfma_f32_16x16x32_bf16 v[82:85], v[154:157], v[246:249], v[82:85]
	v_mfma_f32_16x16x32_bf16 v[74:77], v[162:165], v[246:249], v[74:77]
	s_setprio 0
	s_setprio 1
	v_mfma_f32_16x16x32_bf16 v[118:121], v[166:169], v[198:201], v[118:121]
	v_mfma_f32_16x16x32_bf16 v[110:113], v[174:177], v[198:201], v[110:113]
	v_mfma_f32_16x16x32_bf16 v[102:105], v[166:169], v[206:209], v[102:105]
	v_mfma_f32_16x16x32_bf16 v[94:97], v[174:177], v[206:209], v[94:97]
	v_mfma_f32_16x16x32_bf16 v[86:89], v[166:169], v[234:237], v[86:89]
	v_mfma_f32_16x16x32_bf16 v[78:81], v[174:177], v[234:237], v[78:81]
	v_mfma_f32_16x16x32_bf16 v[70:73], v[166:169], v[242:245], v[70:73]
	v_mfma_f32_16x16x32_bf16 v[66:69], v[174:177], v[242:245], v[66:69]
	v_mfma_f32_16x16x32_bf16 v[118:121], v[170:173], v[202:205], v[118:121]
	v_mfma_f32_16x16x32_bf16 v[110:113], v[194:197], v[202:205], v[110:113]
	v_mfma_f32_16x16x32_bf16 v[102:105], v[170:173], v[210:213], v[102:105]
	v_mfma_f32_16x16x32_bf16 v[94:97], v[194:197], v[210:213], v[94:97]
	v_mfma_f32_16x16x32_bf16 v[86:89], v[170:173], v[238:241], v[86:89]
	v_mfma_f32_16x16x32_bf16 v[78:81], v[194:197], v[238:241], v[78:81]
	v_mfma_f32_16x16x32_bf16 v[70:73], v[170:173], v[246:249], v[70:73]
	v_mfma_f32_16x16x32_bf16 v[66:69], v[194:197], v[246:249], v[66:69]
	s_setprio 0
	s_barrier
	s_add_i32 s58, s58, s26
	s_mov_b32 m0, s58
	ds_read_b128 v[198:201], v153 offset:16384
	ds_read_b128 v[202:205], v153 offset:17408
	ds_read_b128 v[206:209], v153 offset:18432
	ds_read_b128 v[210:213], v153 offset:19456
	ds_read_b128 v[234:237], v153 offset:20480
	ds_read_b128 v[238:241], v153 offset:21504
	ds_read_b128 v[242:245], v153 offset:22528
	ds_read_b128 v[246:249], v153 offset:23552
	global_load_lds_dwordx4 v0, s[20:21]
	s_add_i32 m0, s58, 0x2000
	s_add_u32 s58, s20, 0x80000
	s_addc_u32 s59, s21, 0
	s_add_i32 s75, s75, s26
	global_load_lds_dwordx4 v130, s[20:21]
	s_mov_b32 m0, s75
	s_nop 0
	global_load_lds_dwordx4 v0, s[58:59]
	s_add_i32 m0, s75, 0x2000
	s_nop 0
	global_load_lds_dwordx4 v130, s[58:59]
	s_mov_b32 m0, s27
	s_nop 0
	global_load_lds_dwordx4 v134, s[22:23]
	s_mov_b32 m0, s28
	s_nop 0
	global_load_lds_dwordx4 v132, s[22:23]
	s_nop 0
	s_nop 0
	s_nop 0
	s_nop 0
	s_nop 0
	s_nop 0
	s_waitcnt vmcnt(8)
	s_waitcnt lgkmcnt(0)
	s_barrier
	s_setprio 1
	s_waitcnt lgkmcnt(0)
	v_mfma_f32_16x16x32_bf16 v[62:65], v[140:143], v[198:201], v[62:65]
	v_mfma_f32_16x16x32_bf16 v[58:61], v[158:161], v[198:201], v[58:61]
	v_mfma_f32_16x16x32_bf16 v[50:53], v[140:143], v[206:209], v[50:53]
	v_mfma_f32_16x16x32_bf16 v[42:45], v[158:161], v[206:209], v[42:45]
	v_mfma_f32_16x16x32_bf16 v[34:37], v[140:143], v[234:237], v[34:37]
	v_mfma_f32_16x16x32_bf16 v[26:29], v[158:161], v[234:237], v[26:29]
	v_mfma_f32_16x16x32_bf16 v[18:21], v[140:143], v[242:245], v[18:21]
	v_mfma_f32_16x16x32_bf16 v[10:13], v[158:161], v[242:245], v[10:13]
	v_mfma_f32_16x16x32_bf16 v[62:65], v[154:157], v[202:205], v[62:65]
	v_mfma_f32_16x16x32_bf16 v[58:61], v[162:165], v[202:205], v[58:61]
	v_mfma_f32_16x16x32_bf16 v[50:53], v[154:157], v[210:213], v[50:53]
	v_mfma_f32_16x16x32_bf16 v[42:45], v[162:165], v[210:213], v[42:45]
	v_mfma_f32_16x16x32_bf16 v[34:37], v[154:157], v[238:241], v[34:37]
	v_mfma_f32_16x16x32_bf16 v[26:29], v[162:165], v[238:241], v[26:29]
	v_mfma_f32_16x16x32_bf16 v[18:21], v[154:157], v[246:249], v[18:21]
	v_mfma_f32_16x16x32_bf16 v[10:13], v[162:165], v[246:249], v[10:13]
	s_setprio 0
	s_setprio 1
	v_mfma_f32_16x16x32_bf16 v[54:57], v[166:169], v[198:201], v[54:57]
	v_mfma_f32_16x16x32_bf16 v[46:49], v[174:177], v[198:201], v[46:49]
	v_mfma_f32_16x16x32_bf16 v[38:41], v[166:169], v[206:209], v[38:41]
	v_mfma_f32_16x16x32_bf16 v[30:33], v[174:177], v[206:209], v[30:33]
	v_mfma_f32_16x16x32_bf16 v[22:25], v[166:169], v[234:237], v[22:25]
	v_mfma_f32_16x16x32_bf16 v[14:17], v[174:177], v[234:237], v[14:17]
	v_mfma_f32_16x16x32_bf16 v[6:9], v[166:169], v[242:245], v[6:9]
	v_mfma_f32_16x16x32_bf16 v[2:5], v[174:177], v[242:245], v[2:5]
	v_mfma_f32_16x16x32_bf16 v[54:57], v[170:173], v[202:205], v[54:57]
	v_mfma_f32_16x16x32_bf16 v[46:49], v[194:197], v[202:205], v[46:49]
	v_mfma_f32_16x16x32_bf16 v[38:41], v[170:173], v[210:213], v[38:41]
	v_mfma_f32_16x16x32_bf16 v[30:33], v[194:197], v[210:213], v[30:33]
	v_mfma_f32_16x16x32_bf16 v[22:25], v[170:173], v[238:241], v[22:25]
	v_mfma_f32_16x16x32_bf16 v[14:17], v[194:197], v[238:241], v[14:17]
	v_mfma_f32_16x16x32_bf16 v[6:9], v[170:173], v[246:249], v[6:9]
	v_mfma_f32_16x16x32_bf16 v[2:5], v[194:197], v[246:249], v[2:5]
	s_setprio 0
	s_barrier
; #define PG8_STAGE(bufoff, gbase, voff) do { _Pragma("unroll") for (int _i = 0; _i < 2; ++_i) \
;         __builtin_amdgcn_global_load_lds((const unsigned*)((const char*)(gbase) + (voff)[_i]), (LAS unsigned*)(lds + (bufoff) + ldsw + _i * 8192), 16, 0, 0); } while (0)
; #define PG8_LDA(dst, b, h) do { _Pragma("unroll") for (int m = 0; m < 4; ++m) _Pragma("unroll") for (int k = 0; k < 2; ++k) dst[m][k] = *(const LAS bf16x8*)(lds + PG8_SA(b, h) + aoff + m * 2048 + k * 1024); } while (0)
; #define PG8_LDB(dst, b, h) do { _Pragma("unroll") for (int n = 0; n < 2; ++n) _Pragma("unroll") for (int k = 0; k < 2; ++k) dst[n][k] = *(const LAS bf16x8*)(lds + PG8_SB(b, h) + boff + n * 2048 + k * 1024); } while (0)
; #define PG8_MMA(ai, bj, At, Bt) do { __builtin_amdgcn_s_setprio(1); _Pragma("unroll") for (int m = 0; m < 4; ++m) _Pragma("unroll") for (int n = 0; n < 2; ++n) _Pragma("unroll") for (int k = 0; k < 2; ++k) \
;         acc[ai][bj][m][n] = __builtin_amdgcn_mfma_f32_16x16x32_bf16(Bt[n][k], At[m][k], acc[ai][bj][m][n], 0, 0, 0); __builtin_amdgcn_s_setprio(0); } while (0)
; #define PG8_WAIT_V(n) asm volatile("s_waitcnt vmcnt(" #n ")" ::: "memory")
; #define PG8_WAIT_L(n) asm volatile("s_waitcnt lgkmcnt(" #n ")" ::: "memory")
; #define PG8_BAR __builtin_amdgcn_s_barrier()
; #define PG8_SCHED __builtin_amdgcn_sched_barrier(0)
; template <class Epi, class Sched, bool ALIGN_EPI = true, bool SP2 = true>
; __device__ __forceinline__ void gemm_phase(LAS unsigned char* lds, const Gemm g, const Sched& S, const Epi& E) {
;     ...
;             PG8_LDB(B0, 1, 0); PG8_LDB(B1, 1, 1); PG8_SCHED; PG8_LDA(At, 1, 0); PG8_STAGE(PG8_SA(0, 1), a2 + hstep, voffA);
;             PG8_WAIT_V(8); PG8_WAIT_L(0); PG8_BAR; PG8_MMA(0, 0, At, B0); PG8_MMA(0, 1, At, B1); PG8_BAR; PG8_SCHED;
;             PG8_LDA(At, 1, 1); PG8_STAGE(PG8_SB(1, 0), b3, voffB); PG8_STAGE(PG8_SB(1, 1), b3 + hstep, voffB); PG8_STAGE(PG8_SA(1, 0), a3, voffA);
;             PG8_WAIT_V(8); PG8_WAIT_L(0); PG8_BAR; PG8_MMA(1, 0, At, B0); PG8_MMA(1, 1, At, B1); PG8_BAR; PG8_SCHED;
;     ...
;         if constexpr (ALIGN_EPI) { if (wr == 0) PG8_BAR; }
	s_add_i32 s58, 0, 0x18000
	v_add_u32_e32 v144, s58, v147
	s_add_i32 s59, 0, 0x1c000
	ds_read_b128 v[140:143], v144
	ds_read_b128 v[154:157], v144 offset:1024
	ds_read_b128 v[158:161], v144 offset:2048
	ds_read_b128 v[162:165], v144 offset:3072
	ds_read_b128 v[166:169], v144 offset:16384
	ds_read_b128 v[170:173], v144 offset:17408
	ds_read_b128 v[174:177], v144 offset:18432
	ds_read_b128 v[194:197], v144 offset:19456
	s_add_u32 s22, s22, 0x80000
	s_addc_u32 s23, s23, 0
	s_mov_b32 m0, s29
	ds_read_b128 v[198:201], v153 offset:32768
	ds_read_b128 v[202:205], v153 offset:33792
	ds_read_b128 v[206:209], v153 offset:34816
	ds_read_b128 v[210:213], v153 offset:35840
	ds_read_b128 v[234:237], v153 offset:36864
	ds_read_b128 v[238:241], v153 offset:37888
	ds_read_b128 v[242:245], v153 offset:38912
	ds_read_b128 v[246:249], v153 offset:39936
	global_load_lds_dwordx4 v134, s[22:23]
	s_mov_b32 m0, s30
	s_nop 0
	global_load_lds_dwordx4 v132, s[22:23]
	s_nop 0
	s_nop 0
	s_nop 0
	s_nop 0
	s_nop 0
	s_nop 0
	s_waitcnt vmcnt(8)
	s_waitcnt lgkmcnt(0)
	s_barrier
	s_setprio 1
	s_waitcnt lgkmcnt(0)
	v_mfma_f32_16x16x32_bf16 v[126:129], v[140:143], v[198:201], v[126:129]
	v_mfma_f32_16x16x32_bf16 v[122:125], v[158:161], v[198:201], v[122:125]
	v_mfma_f32_16x16x32_bf16 v[114:117], v[140:143], v[206:209], v[114:117]
	v_mfma_f32_16x16x32_bf16 v[106:109], v[158:161], v[206:209], v[106:109]
	v_mfma_f32_16x16x32_bf16 v[98:101], v[140:143], v[234:237], v[98:101]
	v_mfma_f32_16x16x32_bf16 v[90:93], v[158:161], v[234:237], v[90:93]
	v_mfma_f32_16x16x32_bf16 v[82:85], v[140:143], v[242:245], v[82:85]
	v_mfma_f32_16x16x32_bf16 v[74:77], v[158:161], v[242:245], v[74:77]
	v_mfma_f32_16x16x32_bf16 v[126:129], v[154:157], v[202:205], v[126:129]
	v_mfma_f32_16x16x32_bf16 v[122:125], v[162:165], v[202:205], v[122:125]
	v_mfma_f32_16x16x32_bf16 v[114:117], v[154:157], v[210:213], v[114:117]
	v_mfma_f32_16x16x32_bf16 v[106:109], v[162:165], v[210:213], v[106:109]
	v_mfma_f32_16x16x32_bf16 v[98:101], v[154:157], v[238:241], v[98:101]
	v_mfma_f32_16x16x32_bf16 v[90:93], v[162:165], v[238:241], v[90:93]
	v_mfma_f32_16x16x32_bf16 v[82:85], v[154:157], v[246:249], v[82:85]
	v_mfma_f32_16x16x32_bf16 v[74:77], v[162:165], v[246:249], v[74:77]
	s_setprio 0
	s_setprio 1
	v_mfma_f32_16x16x32_bf16 v[118:121], v[166:169], v[198:201], v[118:121]
	v_mfma_f32_16x16x32_bf16 v[110:113], v[174:177], v[198:201], v[110:113]
	v_mfma_f32_16x16x32_bf16 v[102:105], v[166:169], v[206:209], v[102:105]
	v_mfma_f32_16x16x32_bf16 v[94:97], v[174:177], v[206:209], v[94:97]
	v_mfma_f32_16x16x32_bf16 v[86:89], v[166:169], v[234:237], v[86:89]
	v_mfma_f32_16x16x32_bf16 v[78:81], v[174:177], v[234:237], v[78:81]
	v_mfma_f32_16x16x32_bf16 v[70:73], v[166:169], v[242:245], v[70:73]
	v_mfma_f32_16x16x32_bf16 v[66:69], v[174:177], v[242:245], v[66:69]
	v_mfma_f32_16x16x32_bf16 v[118:121], v[170:173], v[202:205], v[118:121]
	v_mfma_f32_16x16x32_bf16 v[110:113], v[194:197], v[202:205], v[110:113]
	v_mfma_f32_16x16x32_bf16 v[102:105], v[170:173], v[210:213], v[102:105]
	v_mfma_f32_16x16x32_bf16 v[94:97], v[194:197], v[210:213], v[94:97]
	v_mfma_f32_16x16x32_bf16 v[86:89], v[170:173], v[238:241], v[86:89]
	v_mfma_f32_16x16x32_bf16 v[78:81], v[194:197], v[238:241], v[78:81]
	v_mfma_f32_16x16x32_bf16 v[70:73], v[170:173], v[246:249], v[70:73]
	v_mfma_f32_16x16x32_bf16 v[66:69], v[194:197], v[246:249], v[66:69]
	s_setprio 0
	s_barrier
	s_add_i32 s32, s58, s26
	s_add_u32 s20, s20, s92
	s_addc_u32 s21, s21, s93
	s_mov_b32 m0, s32
	ds_read_b128 v[198:201], v153 offset:49152
	ds_read_b128 v[202:205], v153 offset:50176
	ds_read_b128 v[206:209], v153 offset:51200
	ds_read_b128 v[210:213], v153 offset:52224
	ds_read_b128 v[234:237], v153 offset:53248
	ds_read_b128 v[238:241], v153 offset:54272
	ds_read_b128 v[242:245], v153 offset:55296
	ds_read_b128 v[246:249], v153 offset:56320
	global_load_lds_dwordx4 v0, s[20:21]
	s_add_i32 m0, s32, 0x2000
	s_add_i32 s32, s59, s26
	global_load_lds_dwordx4 v130, s[20:21]
	s_add_u32 s20, s20, 0x80000
	s_addc_u32 s21, s21, 0
	s_mov_b32 m0, s32
	s_nop 0
	global_load_lds_dwordx4 v0, s[20:21]
	s_add_i32 m0, s32, 0x2000
	s_nop 0
	global_load_lds_dwordx4 v130, s[20:21]
	s_add_u32 s22, s22, 0xfff80080
	s_addc_u32 s23, s23, -1
	s_mov_b32 m0, s31
	s_nop 0
	global_load_lds_dwordx4 v134, s[22:23]
	s_mov_b32 m0, s34
	s_nop 0
	global_load_lds_dwordx4 v132, s[22:23]
	s_nop 0
	s_nop 0
	s_nop 0
	s_nop 0
	s_nop 0
	s_nop 0
	s_waitcnt vmcnt(8)
	s_waitcnt lgkmcnt(0)
	s_barrier
	s_setprio 1
	s_waitcnt lgkmcnt(0)
	v_mfma_f32_16x16x32_bf16 v[62:65], v[140:143], v[198:201], v[62:65]
	v_mfma_f32_16x16x32_bf16 v[58:61], v[158:161], v[198:201], v[58:61]
	v_mfma_f32_16x16x32_bf16 v[50:53], v[140:143], v[206:209], v[50:53]
	v_mfma_f32_16x16x32_bf16 v[42:45], v[158:161], v[206:209], v[42:45]
	v_mfma_f32_16x16x32_bf16 v[34:37], v[140:143], v[234:237], v[34:37]
	v_mfma_f32_16x16x32_bf16 v[26:29], v[158:161], v[234:237], v[26:29]
	v_mfma_f32_16x16x32_bf16 v[18:21], v[140:143], v[242:245], v[18:21]
	v_mfma_f32_16x16x32_bf16 v[10:13], v[158:161], v[242:245], v[10:13]
	v_mfma_f32_16x16x32_bf16 v[62:65], v[154:157], v[202:205], v[62:65]
	v_mfma_f32_16x16x32_bf16 v[58:61], v[162:165], v[202:205], v[58:61]
	v_mfma_f32_16x16x32_bf16 v[50:53], v[154:157], v[210:213], v[50:53]
	v_mfma_f32_16x16x32_bf16 v[42:45], v[162:165], v[210:213], v[42:45]
	v_mfma_f32_16x16x32_bf16 v[34:37], v[154:157], v[238:241], v[34:37]
	v_mfma_f32_16x16x32_bf16 v[26:29], v[162:165], v[238:241], v[26:29]
	v_mfma_f32_16x16x32_bf16 v[18:21], v[154:157], v[246:249], v[18:21]
	v_mfma_f32_16x16x32_bf16 v[10:13], v[162:165], v[246:249], v[10:13]
	s_setprio 0
	s_setprio 1
	v_mfma_f32_16x16x32_bf16 v[54:57], v[166:169], v[198:201], v[54:57]
	v_mfma_f32_16x16x32_bf16 v[46:49], v[174:177], v[198:201], v[46:49]
	v_mfma_f32_16x16x32_bf16 v[38:41], v[166:169], v[206:209], v[38:41]
	v_mfma_f32_16x16x32_bf16 v[30:33], v[174:177], v[206:209], v[30:33]
	v_mfma_f32_16x16x32_bf16 v[22:25], v[166:169], v[234:237], v[22:25]
	v_mfma_f32_16x16x32_bf16 v[14:17], v[174:177], v[234:237], v[14:17]
	v_mfma_f32_16x16x32_bf16 v[6:9], v[166:169], v[242:245], v[6:9]
	v_mfma_f32_16x16x32_bf16 v[2:5], v[174:177], v[242:245], v[2:5]
	v_mfma_f32_16x16x32_bf16 v[54:57], v[170:173], v[202:205], v[54:57]
	v_mfma_f32_16x16x32_bf16 v[46:49], v[194:197], v[202:205], v[46:49]
	v_mfma_f32_16x16x32_bf16 v[38:41], v[170:173], v[210:213], v[38:41]
	v_mfma_f32_16x16x32_bf16 v[30:33], v[194:197], v[210:213], v[30:33]
	v_mfma_f32_16x16x32_bf16 v[22:25], v[170:173], v[238:241], v[22:25]
	v_mfma_f32_16x16x32_bf16 v[14:17], v[194:197], v[238:241], v[14:17]
	v_mfma_f32_16x16x32_bf16 v[6:9], v[170:173], v[246:249], v[6:9]
	v_mfma_f32_16x16x32_bf16 v[2:5], v[194:197], v[246:249], v[2:5]
	s_setprio 0
	s_barrier
	s_add_i32 s74, s74, 2
	s_add_u32 s16, s16, 0x100
	s_addc_u32 s17, s17, 0
	s_add_u32 s72, s72, 0x100
	s_addc_u32 s73, s73, 0
	s_cmp_gt_u32 s74, 29
	s_cbranch_scc0 .LBB0_306
	s_and_b64 vcc, exec, s[4:5]
	s_cbranch_vccz .LBB0_309
	s_barrier

;     __device__ bool next(int i, Unit& u) const { if (!so.next(i >> 1, u)) return false; u.kind = i & 1; return true; }
; #define PG8_STAGE(bufoff, gbase, voff) do { _Pragma("unroll") for (int _i = 0; _i < 2; ++_i) \
;         __builtin_amdgcn_global_load_lds((const unsigned*)((const char*)(gbase) + (voff)[_i]), (LAS unsigned*)(lds + (bufoff) + ldsw + _i * 8192), 16, 0, 0); } while (0)
; #define PG8_LDA(dst, b, h) do { _Pragma("unroll") for (int m = 0; m < 4; ++m) _Pragma("unroll") for (int k = 0; k < 2; ++k) dst[m][k] = *(const LAS bf16x8*)(lds + PG8_SA(b, h) + aoff + m * 2048 + k * 1024); } while (0)
; #define PG8_LDB(dst, b, h) do { _Pragma("unroll") for (int n = 0; n < 2; ++n) _Pragma("unroll") for (int k = 0; k < 2; ++k) dst[n][k] = *(const LAS bf16x8*)(lds + PG8_SB(b, h) + boff + n * 2048 + k * 1024); } while (0)
; #define PG8_WAIT_V(n) asm volatile("s_waitcnt vmcnt(" #n ")" ::: "memory")
; #define PG8_WAIT_L(n) asm volatile("s_waitcnt lgkmcnt(" #n ")" ::: "memory")
; #define PG8_BAR __builtin_amdgcn_s_barrier()
; #define PG8_SCHED __builtin_amdgcn_sched_barrier(0)
; template <class Epi, class Sched, bool ALIGN_EPI = true, bool SP2 = true>
; __device__ __forceinline__ void gemm_phase(LAS unsigned char* lds, const Gemm g, const Sched& S, const Epi& E) {
;     ...
;         const bool has_next = S.next(ui + 1, nxt);
;         const char* nA = has_next ? (const char*)(nxt.kind ? g.A1 : g.A0) + (size_t)nxt.pm * tstep : cA; const char* nB = has_next ? (const char*)(nxt.kind ? g.B1 : g.B0) + (size_t)nxt.pn * tstep : cB;
;         for (int t = 0; t < nt; t += 2) {
;             const bool last = (t == nt - 2);
;             const char* a1 = cA + (size_t)(t + 1) * kstep;
;             const char* a2 = last ? nA : cA + (size_t)(t + 2) * kstep; const char* b2 = last ? nB : cB + (size_t)(t + 2) * kstep;
;             const char* a3 = a2 + kstep; const char* b3 = b2 + kstep;
;             if constexpr (SP2) {
;             PG8_LDB(B0, 0, 0); PG8_LDB(B1, 0, 1); PG8_SCHED; PG8_LDA(At, 0, 0); PG8_STAGE(PG8_SA(1, 1), a1 + hstep, voffA);
;             PG8_WAIT_V(8); PG8_WAIT_L(0); PG8_BAR; PG8_MMA(0, 0, At, B0); PG8_MMA(0, 1, At, B1); PG8_BAR; PG8_SCHED;
;             PG8_LDA(At, 0, 1); PG8_STAGE(PG8_SB(0, 0), b2, voffB); PG8_STAGE(PG8_SB(0, 1), b2 + hstep, voffB); PG8_STAGE(PG8_SA(0, 0), a2, voffA);
.LBB0_870:
	s_ashr_i32 s17, s16, 31
	s_lshl_b64 s[18:19], s[16:17], 20
	s_add_u32 s18, s88, s18
	s_addc_u32 s19, s89, s19
	s_and_b64 s[20:21], s[8:9], exec
	s_cselect_b32 s17, s19, s5
	s_cselect_b32 s70, s18, s4
	s_ashr_i32 s15, s14, 31
	s_lshl_b64 s[20:21], s[14:15], 20
	s_add_u32 s20, s24, s20
	s_addc_u32 s21, s25, s21
	s_and_b64 s[22:23], s[8:9], exec
	s_cselect_b32 s15, s21, s7
	s_cselect_b32 s71, s20, s6
	s_add_u32 s4, s4, 0x80080
	s_addc_u32 s5, s5, 0
	s_add_u32 s72, s6, 0x100
	s_addc_u32 s73, s7, 0
	s_mov_b32 s74, -2
	s_add_u32 s6, s4, 0xfff80080
	s_addc_u32 s7, s5, -1
	s_add_i32 s58, 0, 0x10000
	s_cmp_eq_u32 s74, 28
	s_cselect_b32 s23, s17, s7
	s_cselect_b32 s22, s70, s6
	v_add_u32_e32 v148, s58, v153
	s_cselect_b32 s7, s15, s73
	s_cselect_b32 s6, s71, s72
	s_add_i32 s75, 0, 0x14000
	ds_read_b128 v[140:143], v148
	ds_read_b128 v[144:147], v148 offset:1024
	ds_read_b128 v[160:163], v148 offset:2048
	ds_read_b128 v[164:167], v148 offset:3072
	ds_read_b128 v[168:171], v148 offset:16384
	ds_read_b128 v[172:175], v148 offset:17408
	ds_read_b128 v[176:179], v148 offset:18432
	ds_read_b128 v[194:197], v148 offset:19456
	s_add_i32 m0, s27, 0xc000
	ds_read_b128 v[198:201], v159
	ds_read_b128 v[202:205], v159 offset:1024
	ds_read_b128 v[206:209], v159 offset:2048
	ds_read_b128 v[210:213], v159 offset:3072
	ds_read_b128 v[234:237], v159 offset:4096
	ds_read_b128 v[238:241], v159 offset:5120
	ds_read_b128 v[242:245], v159 offset:6144
	ds_read_b128 v[246:249], v159 offset:7168
	global_load_lds_dwordx4 v136, s[4:5]
	s_add_i32 m0, s27, 0xe000
	s_nop 0
	global_load_lds_dwordx4 v138, s[4:5]
	s_nop 0
	s_nop 0
	s_nop 0
	s_nop 0
	s_nop 0
	s_nop 0
	s_waitcnt vmcnt(8)
	s_waitcnt lgkmcnt(0)
	s_barrier
	s_setprio 1
	s_waitcnt lgkmcnt(0)
	v_mfma_f32_16x16x32_bf16 v[126:129], v[140:143], v[198:201], 0
	v_mfma_f32_16x16x32_bf16 v[118:121], v[160:163], v[198:201], 0
	v_mfma_f32_16x16x32_bf16 v[110:113], v[140:143], v[206:209], 0
	v_mfma_f32_16x16x32_bf16 v[102:105], v[160:163], v[206:209], 0
	v_mfma_f32_16x16x32_bf16 v[94:97], v[140:143], v[234:237], 0
	v_mfma_f32_16x16x32_bf16 v[86:89], v[160:163], v[234:237], 0
	v_mfma_f32_16x16x32_bf16 v[78:81], v[140:143], v[242:245], 0
	v_mfma_f32_16x16x32_bf16 v[70:73], v[160:163], v[242:245], 0
	v_mfma_f32_16x16x32_bf16 v[126:129], v[144:147], v[202:205], v[126:129]
	v_mfma_f32_16x16x32_bf16 v[118:121], v[164:167], v[202:205], v[118:121]
	v_mfma_f32_16x16x32_bf16 v[110:113], v[144:147], v[210:213], v[110:113]
	v_mfma_f32_16x16x32_bf16 v[102:105], v[164:167], v[210:213], v[102:105]
	v_mfma_f32_16x16x32_bf16 v[94:97], v[144:147], v[238:241], v[94:97]
	v_mfma_f32_16x16x32_bf16 v[86:89], v[164:167], v[238:241], v[86:89]
	v_mfma_f32_16x16x32_bf16 v[78:81], v[144:147], v[246:249], v[78:81]
	v_mfma_f32_16x16x32_bf16 v[70:73], v[164:167], v[246:249], v[70:73]
	s_setprio 0
	s_setprio 1
	v_mfma_f32_16x16x32_bf16 v[122:125], v[168:171], v[198:201], 0
	v_mfma_f32_16x16x32_bf16 v[114:117], v[176:179], v[198:201], 0
	v_mfma_f32_16x16x32_bf16 v[106:109], v[168:171], v[206:209], 0
	v_mfma_f32_16x16x32_bf16 v[98:101], v[176:179], v[206:209], 0
	v_mfma_f32_16x16x32_bf16 v[90:93], v[168:171], v[234:237], 0
	v_mfma_f32_16x16x32_bf16 v[82:85], v[176:179], v[234:237], 0
	v_mfma_f32_16x16x32_bf16 v[74:77], v[168:171], v[242:245], 0
	v_mfma_f32_16x16x32_bf16 v[66:69], v[176:179], v[242:245], 0
	v_mfma_f32_16x16x32_bf16 v[122:125], v[172:175], v[202:205], v[122:125]
	v_mfma_f32_16x16x32_bf16 v[114:117], v[194:197], v[202:205], v[114:117]
	v_mfma_f32_16x16x32_bf16 v[106:109], v[172:175], v[210:213], v[106:109]
	v_mfma_f32_16x16x32_bf16 v[98:101], v[194:197], v[210:213], v[98:101]
	v_mfma_f32_16x16x32_bf16 v[90:93], v[172:175], v[238:241], v[90:93]
	v_mfma_f32_16x16x32_bf16 v[82:85], v[194:197], v[238:241], v[82:85]
	v_mfma_f32_16x16x32_bf16 v[74:77], v[172:175], v[246:249], v[74:77]
	v_mfma_f32_16x16x32_bf16 v[66:69], v[194:197], v[246:249], v[66:69]
	s_setprio 0
	s_barrier
	s_add_i32 s58, s58, s26
	s_mov_b32 m0, s58
	ds_read_b128 v[198:201], v159 offset:16384
	ds_read_b128 v[202:205], v159 offset:17408
	ds_read_b128 v[206:209], v159 offset:18432
	ds_read_b128 v[210:213], v159 offset:19456
	ds_read_b128 v[234:237], v159 offset:20480
	ds_read_b128 v[238:241], v159 offset:21504
	ds_read_b128 v[242:245], v159 offset:22528
	ds_read_b128 v[246:249], v159 offset:23552
	global_load_lds_dwordx4 v0, s[6:7]
	s_add_i32 m0, s58, 0x2000
	s_add_u32 s58, s6, 0x80000
	s_addc_u32 s59, s7, 0
	s_add_i32 s75, s75, s26
	global_load_lds_dwordx4 v130, s[6:7]
	s_mov_b32 m0, s75
	s_nop 0
	global_load_lds_dwordx4 v0, s[58:59]
	s_add_i32 m0, s75, 0x2000
	s_nop 0
	global_load_lds_dwordx4 v130, s[58:59]
	s_mov_b32 m0, s27
	s_nop 0
	global_load_lds_dwordx4 v134, s[22:23]
	s_mov_b32 m0, s28
	s_nop 0
	global_load_lds_dwordx4 v132, s[22:23]
	s_nop 0
	s_nop 0
	s_nop 0
	s_nop 0
	s_nop 0
	s_nop 0
	s_waitcnt vmcnt(8)
	s_waitcnt lgkmcnt(0)
	s_barrier
; #define PG8_STAGE(bufoff, gbase, voff) do { _Pragma("unroll") for (int _i = 0; _i < 2; ++_i) \
;         __builtin_amdgcn_global_load_lds((const unsigned*)((const char*)(gbase) + (voff)[_i]), (LAS unsigned*)(lds + (bufoff) + ldsw + _i * 8192), 16, 0, 0); } while (0)
; #define PG8_LDA(dst, b, h) do { _Pragma("unroll") for (int m = 0; m < 4; ++m) _Pragma("unroll") for (int k = 0; k < 2; ++k) dst[m][k] = *(const LAS bf16x8*)(lds + PG8_SA(b, h) + aoff + m * 2048 + k * 1024); } while (0)
; #define PG8_LDB(dst, b, h) do { _Pragma("unroll") for (int n = 0; n < 2; ++n) _Pragma("unroll") for (int k = 0; k < 2; ++k) dst[n][k] = *(const LAS bf16x8*)(lds + PG8_SB(b, h) + boff + n * 2048 + k * 1024); } while (0)
; #define PG8_MMA(ai, bj, At, Bt) do { __builtin_amdgcn_s_setprio(1); _Pragma("unroll") for (int m = 0; m < 4; ++m) _Pragma("unroll") for (int n = 0; n < 2; ++n) _Pragma("unroll") for (int k = 0; k < 2; ++k) \
;         acc[ai][bj][m][n] = __builtin_amdgcn_mfma_f32_16x16x32_bf16(Bt[n][k], At[m][k], acc[ai][bj][m][n], 0, 0, 0); __builtin_amdgcn_s_setprio(0); } while (0)
; #define PG8_WAIT_V(n) asm volatile("s_waitcnt vmcnt(" #n ")" ::: "memory")
; #define PG8_WAIT_L(n) asm volatile("s_waitcnt lgkmcnt(" #n ")" ::: "memory")
; #define PG8_BAR __builtin_amdgcn_s_barrier()
; #define PG8_SCHED __builtin_amdgcn_sched_barrier(0)
; template <class Epi, class Sched, bool ALIGN_EPI = true, bool SP2 = true>
; __device__ __forceinline__ void gemm_phase(LAS unsigned char* lds, const Gemm g, const Sched& S, const Epi& E) {
;     ...
;             PG8_WAIT_V(8); PG8_WAIT_L(0); PG8_BAR; PG8_MMA(1, 0, At, B0); PG8_MMA(1, 1, At, B1); PG8_BAR; PG8_SCHED;
;             PG8_LDB(B0, 1, 0); PG8_LDB(B1, 1, 1); PG8_SCHED; PG8_LDA(At, 1, 0); PG8_STAGE(PG8_SA(0, 1), a2 + hstep, voffA);
;             PG8_WAIT_V(8); PG8_WAIT_L(0); PG8_BAR; PG8_MMA(0, 0, At, B0); PG8_MMA(0, 1, At, B1); PG8_BAR; PG8_SCHED;
	s_setprio 1
	s_waitcnt lgkmcnt(0)
	v_mfma_f32_16x16x32_bf16 v[62:65], v[140:143], v[198:201], 0
	v_mfma_f32_16x16x32_bf16 v[54:57], v[160:163], v[198:201], 0
	v_mfma_f32_16x16x32_bf16 v[46:49], v[140:143], v[206:209], 0
	v_mfma_f32_16x16x32_bf16 v[38:41], v[160:163], v[206:209], 0
	v_mfma_f32_16x16x32_bf16 v[30:33], v[140:143], v[234:237], 0
	v_mfma_f32_16x16x32_bf16 v[22:25], v[160:163], v[234:237], 0
	v_mfma_f32_16x16x32_bf16 v[14:17], v[140:143], v[242:245], 0
	v_mfma_f32_16x16x32_bf16 v[6:9], v[160:163], v[242:245], 0
	v_mfma_f32_16x16x32_bf16 v[62:65], v[144:147], v[202:205], v[62:65]
	v_mfma_f32_16x16x32_bf16 v[54:57], v[164:167], v[202:205], v[54:57]
	v_mfma_f32_16x16x32_bf16 v[46:49], v[144:147], v[210:213], v[46:49]
	v_mfma_f32_16x16x32_bf16 v[38:41], v[164:167], v[210:213], v[38:41]
	v_mfma_f32_16x16x32_bf16 v[30:33], v[144:147], v[238:241], v[30:33]
	v_mfma_f32_16x16x32_bf16 v[22:25], v[164:167], v[238:241], v[22:25]
	v_mfma_f32_16x16x32_bf16 v[14:17], v[144:147], v[246:249], v[14:17]
	v_mfma_f32_16x16x32_bf16 v[6:9], v[164:167], v[246:249], v[6:9]
	s_setprio 0
	s_setprio 1
	v_mfma_f32_16x16x32_bf16 v[58:61], v[168:171], v[198:201], 0
	v_mfma_f32_16x16x32_bf16 v[50:53], v[176:179], v[198:201], 0
	v_mfma_f32_16x16x32_bf16 v[42:45], v[168:171], v[206:209], 0
	v_mfma_f32_16x16x32_bf16 v[34:37], v[176:179], v[206:209], 0
	v_mfma_f32_16x16x32_bf16 v[26:29], v[168:171], v[234:237], 0
	v_mfma_f32_16x16x32_bf16 v[18:21], v[176:179], v[234:237], 0
	v_mfma_f32_16x16x32_bf16 v[10:13], v[168:171], v[242:245], 0
	v_mfma_f32_16x16x32_bf16 v[2:5], v[176:179], v[242:245], 0
	v_mfma_f32_16x16x32_bf16 v[58:61], v[172:175], v[202:205], v[58:61]
	v_mfma_f32_16x16x32_bf16 v[50:53], v[194:197], v[202:205], v[50:53]
	v_mfma_f32_16x16x32_bf16 v[42:45], v[172:175], v[210:213], v[42:45]
	v_mfma_f32_16x16x32_bf16 v[34:37], v[194:197], v[210:213], v[34:37]
	v_mfma_f32_16x16x32_bf16 v[26:29], v[172:175], v[238:241], v[26:29]
	v_mfma_f32_16x16x32_bf16 v[18:21], v[194:197], v[238:241], v[18:21]
	v_mfma_f32_16x16x32_bf16 v[10:13], v[172:175], v[246:249], v[10:13]
	v_mfma_f32_16x16x32_bf16 v[2:5], v[194:197], v[246:249], v[2:5]
	s_setprio 0
	s_barrier
	s_add_i32 s58, 0, 0x18000
	v_add_u32_e32 v150, s58, v153
	s_add_i32 s59, 0, 0x1c000
	ds_read_b128 v[140:143], v150
	ds_read_b128 v[144:147], v150 offset:1024
	ds_read_b128 v[160:163], v150 offset:2048
	ds_read_b128 v[164:167], v150 offset:3072
	ds_read_b128 v[168:171], v150 offset:16384
	ds_read_b128 v[172:175], v150 offset:17408
	ds_read_b128 v[176:179], v150 offset:18432
	ds_read_b128 v[194:197], v150 offset:19456
	s_add_u32 s22, s22, 0x80000
	s_addc_u32 s23, s23, 0
	s_mov_b32 m0, s29
	ds_read_b128 v[198:201], v159 offset:32768
	ds_read_b128 v[202:205], v159 offset:33792
	ds_read_b128 v[206:209], v159 offset:34816
	ds_read_b128 v[210:213], v159 offset:35840
	ds_read_b128 v[234:237], v159 offset:36864
	ds_read_b128 v[238:241], v159 offset:37888
	ds_read_b128 v[242:245], v159 offset:38912
	ds_read_b128 v[246:249], v159 offset:39936
	global_load_lds_dwordx4 v134, s[22:23]
	s_mov_b32 m0, s30
	s_nop 0
	global_load_lds_dwordx4 v132, s[22:23]
	s_nop 0
	s_nop 0
	s_nop 0
	s_nop 0
	s_nop 0
	s_nop 0
	s_waitcnt vmcnt(8)
	s_waitcnt lgkmcnt(0)
	s_barrier
	s_setprio 1
	s_waitcnt lgkmcnt(0)
	v_mfma_f32_16x16x32_bf16 v[126:129], v[140:143], v[198:201], v[126:129]
	v_mfma_f32_16x16x32_bf16 v[118:121], v[160:163], v[198:201], v[118:121]
	v_mfma_f32_16x16x32_bf16 v[110:113], v[140:143], v[206:209], v[110:113]
	v_mfma_f32_16x16x32_bf16 v[102:105], v[160:163], v[206:209], v[102:105]
	v_mfma_f32_16x16x32_bf16 v[94:97], v[140:143], v[234:237], v[94:97]
	v_mfma_f32_16x16x32_bf16 v[86:89], v[160:163], v[234:237], v[86:89]
	v_mfma_f32_16x16x32_bf16 v[78:81], v[140:143], v[242:245], v[78:81]
	v_mfma_f32_16x16x32_bf16 v[70:73], v[160:163], v[242:245], v[70:73]
	v_mfma_f32_16x16x32_bf16 v[126:129], v[144:147], v[202:205], v[126:129]
	v_mfma_f32_16x16x32_bf16 v[118:121], v[164:167], v[202:205], v[118:121]
	v_mfma_f32_16x16x32_bf16 v[110:113], v[144:147], v[210:213], v[110:113]
	v_mfma_f32_16x16x32_bf16 v[102:105], v[164:167], v[210:213], v[102:105]
	v_mfma_f32_16x16x32_bf16 v[94:97], v[144:147], v[238:241], v[94:97]
	v_mfma_f32_16x16x32_bf16 v[86:89], v[164:167], v[238:241], v[86:89]
	v_mfma_f32_16x16x32_bf16 v[78:81], v[144:147], v[246:249], v[78:81]
	v_mfma_f32_16x16x32_bf16 v[70:73], v[164:167], v[246:249], v[70:73]
	s_setprio 0
	s_setprio 1
	v_mfma_f32_16x16x32_bf16 v[122:125], v[168:171], v[198:201], v[122:125]
	v_mfma_f32_16x16x32_bf16 v[114:117], v[176:179], v[198:201], v[114:117]
	v_mfma_f32_16x16x32_bf16 v[106:109], v[168:171], v[206:209], v[106:109]
	v_mfma_f32_16x16x32_bf16 v[98:101], v[176:179], v[206:209], v[98:101]
	v_mfma_f32_16x16x32_bf16 v[90:93], v[168:171], v[234:237], v[90:93]
	v_mfma_f32_16x16x32_bf16 v[82:85], v[176:179], v[234:237], v[82:85]
	v_mfma_f32_16x16x32_bf16 v[74:77], v[168:171], v[242:245], v[74:77]
	v_mfma_f32_16x16x32_bf16 v[66:69], v[176:179], v[242:245], v[66:69]
	v_mfma_f32_16x16x32_bf16 v[122:125], v[172:175], v[202:205], v[122:125]
	v_mfma_f32_16x16x32_bf16 v[114:117], v[194:197], v[202:205], v[114:117]
	v_mfma_f32_16x16x32_bf16 v[106:109], v[172:175], v[210:213], v[106:109]
	v_mfma_f32_16x16x32_bf16 v[98:101], v[194:197], v[210:213], v[98:101]
	v_mfma_f32_16x16x32_bf16 v[90:93], v[172:175], v[238:241], v[90:93]
	v_mfma_f32_16x16x32_bf16 v[82:85], v[194:197], v[238:241], v[82:85]
	v_mfma_f32_16x16x32_bf16 v[74:77], v[172:175], v[246:249], v[74:77]
	v_mfma_f32_16x16x32_bf16 v[66:69], v[194:197], v[246:249], v[66:69]
	s_setprio 0
	s_barrier
; #define PG8_STAGE(bufoff, gbase, voff) do { _Pragma("unroll") for (int _i = 0; _i < 2; ++_i) \
;         __builtin_amdgcn_global_load_lds((const unsigned*)((const char*)(gbase) + (voff)[_i]), (LAS unsigned*)(lds + (bufoff) + ldsw + _i * 8192), 16, 0, 0); } while (0)
; #define PG8_LDA(dst, b, h) do { _Pragma("unroll") for (int m = 0; m < 4; ++m) _Pragma("unroll") for (int k = 0; k < 2; ++k) dst[m][k] = *(const LAS bf16x8*)(lds + PG8_SA(b, h) + aoff + m * 2048 + k * 1024); } while (0)
; #define PG8_LDB(dst, b, h) do { _Pragma("unroll") for (int n = 0; n < 2; ++n) _Pragma("unroll") for (int k = 0; k < 2; ++k) dst[n][k] = *(const LAS bf16x8*)(lds + PG8_SB(b, h) + boff + n * 2048 + k * 1024); } while (0)
; #define PG8_WAIT_V(n) asm volatile("s_waitcnt vmcnt(" #n ")" ::: "memory")
; #define PG8_BAR __builtin_amdgcn_s_barrier()
; template <class Epi, class Sched, bool ALIGN_EPI = true, bool SP2 = true>
; __device__ __forceinline__ void gemm_phase(LAS unsigned char* lds, const Gemm g, const Sched& S, const Epi& E) {
;     ...
;             const bool last = (t == nt - 2);
;             const char* a1 = cA + (size_t)(t + 1) * kstep;
;             const char* a2 = last ? nA : cA + (size_t)(t + 2) * kstep; const char* b2 = last ? nB : cB + (size_t)(t + 2) * kstep;
;             const char* a3 = a2 + kstep; const char* b3 = b2 + kstep;
;             if constexpr (SP2) {
;             PG8_LDB(B0, 0, 0); PG8_LDB(B1, 0, 1); PG8_SCHED; PG8_LDA(At, 0, 0); PG8_STAGE(PG8_SA(1, 1), a1 + hstep, voffA);
;             PG8_WAIT_V(8); PG8_WAIT_L(0); PG8_BAR; PG8_MMA(0, 0, At, B0); PG8_MMA(0, 1, At, B1); PG8_BAR; PG8_SCHED;
;             PG8_LDA(At, 0, 1); PG8_STAGE(PG8_SB(0, 0), b2, voffB); PG8_STAGE(PG8_SB(0, 1), b2 + hstep, voffB); PG8_STAGE(PG8_SA(0, 0), a2, voffA);
;             PG8_WAIT_V(8); PG8_WAIT_L(0); PG8_BAR; PG8_MMA(1, 0, At, B0); PG8_MMA(1, 1, At, B1); PG8_BAR; PG8_SCHED;
;             PG8_LDB(B0, 1, 0); PG8_LDB(B1, 1, 1); PG8_SCHED; PG8_LDA(At, 1, 0); PG8_STAGE(PG8_SA(0, 1), a2 + hstep, voffA);
;             PG8_WAIT_V(8); PG8_WAIT_L(0); PG8_BAR; PG8_MMA(0, 0, At, B0); PG8_MMA(0, 1, At, B1); PG8_BAR; PG8_SCHED;
;             PG8_LDA(At, 1, 1); PG8_STAGE(PG8_SB(1, 0), b3, voffB); PG8_STAGE(PG8_SB(1, 1), b3 + hstep, voffB); PG8_STAGE(PG8_SA(1, 0), a3, voffA);
;             PG8_WAIT_V(8); PG8_WAIT_L(0); PG8_BAR; PG8_MMA(1, 0, At, B0); PG8_MMA(1, 1, At, B1); PG8_BAR; PG8_SCHED;
	s_add_i32 s32, s58, s26
	s_add_u32 s6, s6, s92
	s_addc_u32 s7, s7, s93
	s_mov_b32 m0, s32
	ds_read_b128 v[198:201], v159 offset:49152
	ds_read_b128 v[202:205], v159 offset:50176
	ds_read_b128 v[206:209], v159 offset:51200
	ds_read_b128 v[210:213], v159 offset:52224
	ds_read_b128 v[234:237], v159 offset:53248
	ds_read_b128 v[238:241], v159 offset:54272
	ds_read_b128 v[242:245], v159 offset:55296
	ds_read_b128 v[246:249], v159 offset:56320
	global_load_lds_dwordx4 v0, s[6:7]
	s_add_i32 m0, s32, 0x2000
	s_add_i32 s32, s59, s26
	global_load_lds_dwordx4 v130, s[6:7]
	s_add_u32 s6, s6, 0x80000
	s_addc_u32 s7, s7, 0
	s_mov_b32 m0, s32
	s_nop 0
	global_load_lds_dwordx4 v0, s[6:7]
	s_add_i32 m0, s32, 0x2000
	s_nop 0
	global_load_lds_dwordx4 v130, s[6:7]
	s_add_u32 s22, s22, 0xfff80080
	s_addc_u32 s23, s23, -1
	s_mov_b32 m0, s31
	s_nop 0
	global_load_lds_dwordx4 v134, s[22:23]
	s_mov_b32 m0, s34
	s_nop 0
	global_load_lds_dwordx4 v132, s[22:23]
	s_nop 0
	s_nop 0
	s_nop 0
	s_nop 0
	s_nop 0
	s_nop 0
	s_waitcnt vmcnt(8)
	s_waitcnt lgkmcnt(0)
	s_barrier
	s_setprio 1
	s_waitcnt lgkmcnt(0)
	v_mfma_f32_16x16x32_bf16 v[62:65], v[140:143], v[198:201], v[62:65]
	v_mfma_f32_16x16x32_bf16 v[54:57], v[160:163], v[198:201], v[54:57]
	v_mfma_f32_16x16x32_bf16 v[46:49], v[140:143], v[206:209], v[46:49]
	v_mfma_f32_16x16x32_bf16 v[38:41], v[160:163], v[206:209], v[38:41]
	v_mfma_f32_16x16x32_bf16 v[30:33], v[140:143], v[234:237], v[30:33]
	v_mfma_f32_16x16x32_bf16 v[22:25], v[160:163], v[234:237], v[22:25]
	v_mfma_f32_16x16x32_bf16 v[14:17], v[140:143], v[242:245], v[14:17]
	v_mfma_f32_16x16x32_bf16 v[6:9], v[160:163], v[242:245], v[6:9]
	v_mfma_f32_16x16x32_bf16 v[62:65], v[144:147], v[202:205], v[62:65]
	v_mfma_f32_16x16x32_bf16 v[54:57], v[164:167], v[202:205], v[54:57]
	v_mfma_f32_16x16x32_bf16 v[46:49], v[144:147], v[210:213], v[46:49]
	v_mfma_f32_16x16x32_bf16 v[38:41], v[164:167], v[210:213], v[38:41]
	v_mfma_f32_16x16x32_bf16 v[30:33], v[144:147], v[238:241], v[30:33]
	v_mfma_f32_16x16x32_bf16 v[22:25], v[164:167], v[238:241], v[22:25]
	v_mfma_f32_16x16x32_bf16 v[14:17], v[144:147], v[246:249], v[14:17]
	v_mfma_f32_16x16x32_bf16 v[6:9], v[164:167], v[246:249], v[6:9]
	s_setprio 0
	s_setprio 1
	v_mfma_f32_16x16x32_bf16 v[58:61], v[168:171], v[198:201], v[58:61]
	v_mfma_f32_16x16x32_bf16 v[50:53], v[176:179], v[198:201], v[50:53]
	v_mfma_f32_16x16x32_bf16 v[42:45], v[168:171], v[206:209], v[42:45]
	v_mfma_f32_16x16x32_bf16 v[34:37], v[176:179], v[206:209], v[34:37]
	v_mfma_f32_16x16x32_bf16 v[26:29], v[168:171], v[234:237], v[26:29]
	v_mfma_f32_16x16x32_bf16 v[18:21], v[176:179], v[234:237], v[18:21]
	v_mfma_f32_16x16x32_bf16 v[10:13], v[168:171], v[242:245], v[10:13]
	v_mfma_f32_16x16x32_bf16 v[2:5], v[176:179], v[242:245], v[2:5]
	v_mfma_f32_16x16x32_bf16 v[58:61], v[172:175], v[202:205], v[58:61]
	v_mfma_f32_16x16x32_bf16 v[50:53], v[194:197], v[202:205], v[50:53]
	v_mfma_f32_16x16x32_bf16 v[42:45], v[172:175], v[210:213], v[42:45]
	v_mfma_f32_16x16x32_bf16 v[34:37], v[194:197], v[210:213], v[34:37]
	v_mfma_f32_16x16x32_bf16 v[26:29], v[172:175], v[238:241], v[26:29]
	v_mfma_f32_16x16x32_bf16 v[18:21], v[194:197], v[238:241], v[18:21]
	v_mfma_f32_16x16x32_bf16 v[10:13], v[172:175], v[246:249], v[10:13]
	v_mfma_f32_16x16x32_bf16 v[2:5], v[194:197], v[246:249], v[2:5]
	s_setprio 0
	s_barrier
	s_add_i32 s74, s74, 2
	s_add_u32 s4, s4, 0x100
	s_addc_u32 s5, s5, 0
	s_add_u32 s72, s72, 0x100
	s_addc_u32 s73, s73, 0
	s_cmp_gt_u32 s74, 29
.LBB0_871:
	s_add_u32 s6, s4, 0xfff80080
	s_addc_u32 s7, s5, -1
	s_add_i32 s58, 0, 0x10000
	s_cmp_eq_u32 s74, 28
	s_cselect_b32 s23, s17, s7
	s_cselect_b32 s22, s70, s6
	v_add_u32_e32 v148, s58, v153
	s_cselect_b32 s7, s15, s73
	s_cselect_b32 s6, s71, s72
	s_add_i32 s75, 0, 0x14000
	ds_read_b128 v[140:143], v148
	ds_read_b128 v[144:147], v148 offset:1024
	ds_read_b128 v[160:163], v148 offset:2048
	ds_read_b128 v[164:167], v148 offset:3072
	ds_read_b128 v[168:171], v148 offset:16384
	ds_read_b128 v[172:175], v148 offset:17408
	ds_read_b128 v[176:179], v148 offset:18432
	ds_read_b128 v[194:197], v148 offset:19456
	s_add_i32 m0, s27, 0xc000
	ds_read_b128 v[198:201], v159
	ds_read_b128 v[202:205], v159 offset:1024
	ds_read_b128 v[206:209], v159 offset:2048
	ds_read_b128 v[210:213], v159 offset:3072
	ds_read_b128 v[234:237], v159 offset:4096
	ds_read_b128 v[238:241], v159 offset:5120
	ds_read_b128 v[242:245], v159 offset:6144
	ds_read_b128 v[246:249], v159 offset:7168
	global_load_lds_dwordx4 v136, s[4:5]
	s_add_i32 m0, s27, 0xe000
	s_nop 0
	global_load_lds_dwordx4 v138, s[4:5]
	s_nop 0
	s_nop 0
	s_nop 0
	s_nop 0
	s_nop 0
	s_nop 0
	s_waitcnt vmcnt(8)
	s_waitcnt lgkmcnt(0)
	s_barrier
; #define PG8_STAGE(bufoff, gbase, voff) do { _Pragma("unroll") for (int _i = 0; _i < 2; ++_i) \
;         __builtin_amdgcn_global_load_lds((const unsigned*)((const char*)(gbase) + (voff)[_i]), (LAS unsigned*)(lds + (bufoff) + ldsw + _i * 8192), 16, 0, 0); } while (0)
; #define PG8_LDA(dst, b, h) do { _Pragma("unroll") for (int m = 0; m < 4; ++m) _Pragma("unroll") for (int k = 0; k < 2; ++k) dst[m][k] = *(const LAS bf16x8*)(lds + PG8_SA(b, h) + aoff + m * 2048 + k * 1024); } while (0)
; #define PG8_MMA(ai, bj, At, Bt) do { __builtin_amdgcn_s_setprio(1); _Pragma("unroll") for (int m = 0; m < 4; ++m) _Pragma("unroll") for (int n = 0; n < 2; ++n) _Pragma("unroll") for (int k = 0; k < 2; ++k) \
;         acc[ai][bj][m][n] = __builtin_amdgcn_mfma_f32_16x16x32_bf16(Bt[n][k], At[m][k], acc[ai][bj][m][n], 0, 0, 0); __builtin_amdgcn_s_setprio(0); } while (0)
; #define PG8_WAIT_V(n) asm volatile("s_waitcnt vmcnt(" #n ")" ::: "memory")
; #define PG8_WAIT_L(n) asm volatile("s_waitcnt lgkmcnt(" #n ")" ::: "memory")
; #define PG8_BAR __builtin_amdgcn_s_barrier()
; #define PG8_SCHED __builtin_amdgcn_sched_barrier(0)
; template <class Epi, class Sched, bool ALIGN_EPI = true, bool SP2 = true>
; __device__ __forceinline__ void gemm_phase(LAS unsigned char* lds, const Gemm g, const Sched& S, const Epi& E) {
;     ...
;             PG8_WAIT_V(8); PG8_WAIT_L(0); PG8_BAR; PG8_MMA(0, 0, At, B0); PG8_MMA(0, 1, At, B1); PG8_BAR; PG8_SCHED;
;             PG8_LDA(At, 0, 1); PG8_STAGE(PG8_SB(0, 0), b2, voffB); PG8_STAGE(PG8_SB(0, 1), b2 + hstep, voffB); PG8_STAGE(PG8_SA(0, 0), a2, voffA);
;             PG8_WAIT_V(8); PG8_WAIT_L(0); PG8_BAR; PG8_MMA(1, 0, At, B0); PG8_MMA(1, 1, At, B1); PG8_BAR; PG8_SCHED;
	s_setprio 1
	s_waitcnt lgkmcnt(0)
	v_mfma_f32_16x16x32_bf16 v[126:129], v[140:143], v[198:201], v[126:129]
	v_mfma_f32_16x16x32_bf16 v[118:121], v[160:163], v[198:201], v[118:121]
	v_mfma_f32_16x16x32_bf16 v[110:113], v[140:143], v[206:209], v[110:113]
	v_mfma_f32_16x16x32_bf16 v[102:105], v[160:163], v[206:209], v[102:105]
	v_mfma_f32_16x16x32_bf16 v[94:97], v[140:143], v[234:237], v[94:97]
	v_mfma_f32_16x16x32_bf16 v[86:89], v[160:163], v[234:237], v[86:89]
	v_mfma_f32_16x16x32_bf16 v[78:81], v[140:143], v[242:245], v[78:81]
	v_mfma_f32_16x16x32_bf16 v[70:73], v[160:163], v[242:245], v[70:73]
	v_mfma_f32_16x16x32_bf16 v[126:129], v[144:147], v[202:205], v[126:129]
	v_mfma_f32_16x16x32_bf16 v[118:121], v[164:167], v[202:205], v[118:121]
	v_mfma_f32_16x16x32_bf16 v[110:113], v[144:147], v[210:213], v[110:113]
	v_mfma_f32_16x16x32_bf16 v[102:105], v[164:167], v[210:213], v[102:105]
	v_mfma_f32_16x16x32_bf16 v[94:97], v[144:147], v[238:241], v[94:97]
	v_mfma_f32_16x16x32_bf16 v[86:89], v[164:167], v[238:241], v[86:89]
	v_mfma_f32_16x16x32_bf16 v[78:81], v[144:147], v[246:249], v[78:81]
	v_mfma_f32_16x16x32_bf16 v[70:73], v[164:167], v[246:249], v[70:73]
	s_setprio 0
	s_setprio 1
	v_mfma_f32_16x16x32_bf16 v[122:125], v[168:171], v[198:201], v[122:125]
	v_mfma_f32_16x16x32_bf16 v[114:117], v[176:179], v[198:201], v[114:117]
	v_mfma_f32_16x16x32_bf16 v[106:109], v[168:171], v[206:209], v[106:109]
	v_mfma_f32_16x16x32_bf16 v[98:101], v[176:179], v[206:209], v[98:101]
	v_mfma_f32_16x16x32_bf16 v[90:93], v[168:171], v[234:237], v[90:93]
	v_mfma_f32_16x16x32_bf16 v[82:85], v[176:179], v[234:237], v[82:85]
	v_mfma_f32_16x16x32_bf16 v[74:77], v[168:171], v[242:245], v[74:77]
	v_mfma_f32_16x16x32_bf16 v[66:69], v[176:179], v[242:245], v[66:69]
	v_mfma_f32_16x16x32_bf16 v[122:125], v[172:175], v[202:205], v[122:125]
	v_mfma_f32_16x16x32_bf16 v[114:117], v[194:197], v[202:205], v[114:117]
	v_mfma_f32_16x16x32_bf16 v[106:109], v[172:175], v[210:213], v[106:109]
	v_mfma_f32_16x16x32_bf16 v[98:101], v[194:197], v[210:213], v[98:101]
	v_mfma_f32_16x16x32_bf16 v[90:93], v[172:175], v[238:241], v[90:93]
	v_mfma_f32_16x16x32_bf16 v[82:85], v[194:197], v[238:241], v[82:85]
	v_mfma_f32_16x16x32_bf16 v[74:77], v[172:175], v[246:249], v[74:77]
	v_mfma_f32_16x16x32_bf16 v[66:69], v[194:197], v[246:249], v[66:69]
	s_setprio 0
	s_barrier
	s_add_i32 s58, s58, s26
	s_mov_b32 m0, s58
	ds_read_b128 v[198:201], v159 offset:16384
	ds_read_b128 v[202:205], v159 offset:17408
	ds_read_b128 v[206:209], v159 offset:18432
	ds_read_b128 v[210:213], v159 offset:19456
	ds_read_b128 v[234:237], v159 offset:20480
	ds_read_b128 v[238:241], v159 offset:21504
	ds_read_b128 v[242:245], v159 offset:22528
	ds_read_b128 v[246:249], v159 offset:23552
	global_load_lds_dwordx4 v0, s[6:7]
	s_add_i32 m0, s58, 0x2000
	s_add_u32 s58, s6, 0x80000
	s_addc_u32 s59, s7, 0
	s_add_i32 s75, s75, s26
	global_load_lds_dwordx4 v130, s[6:7]
	s_mov_b32 m0, s75
	s_nop 0
	global_load_lds_dwordx4 v0, s[58:59]
	s_add_i32 m0, s75, 0x2000
	s_nop 0
	global_load_lds_dwordx4 v130, s[58:59]
	s_mov_b32 m0, s27
	s_nop 0
	global_load_lds_dwordx4 v134, s[22:23]
	s_mov_b32 m0, s28
	s_nop 0
	global_load_lds_dwordx4 v132, s[22:23]
	s_nop 0
	s_nop 0
	s_nop 0
	s_nop 0
	s_nop 0
	s_nop 0
	s_waitcnt vmcnt(8)
	s_waitcnt lgkmcnt(0)
	s_barrier
	s_setprio 1
	s_waitcnt lgkmcnt(0)
	v_mfma_f32_16x16x32_bf16 v[62:65], v[140:143], v[198:201], v[62:65]
	v_mfma_f32_16x16x32_bf16 v[54:57], v[160:163], v[198:201], v[54:57]
	v_mfma_f32_16x16x32_bf16 v[46:49], v[140:143], v[206:209], v[46:49]
	v_mfma_f32_16x16x32_bf16 v[38:41], v[160:163], v[206:209], v[38:41]
	v_mfma_f32_16x16x32_bf16 v[30:33], v[140:143], v[234:237], v[30:33]
	v_mfma_f32_16x16x32_bf16 v[22:25], v[160:163], v[234:237], v[22:25]
	v_mfma_f32_16x16x32_bf16 v[14:17], v[140:143], v[242:245], v[14:17]
	v_mfma_f32_16x16x32_bf16 v[6:9], v[160:163], v[242:245], v[6:9]
	v_mfma_f32_16x16x32_bf16 v[62:65], v[144:147], v[202:205], v[62:65]
	v_mfma_f32_16x16x32_bf16 v[54:57], v[164:167], v[202:205], v[54:57]
	v_mfma_f32_16x16x32_bf16 v[46:49], v[144:147], v[210:213], v[46:49]
	v_mfma_f32_16x16x32_bf16 v[38:41], v[164:167], v[210:213], v[38:41]
	v_mfma_f32_16x16x32_bf16 v[30:33], v[144:147], v[238:241], v[30:33]
	v_mfma_f32_16x16x32_bf16 v[22:25], v[164:167], v[238:241], v[22:25]
	v_mfma_f32_16x16x32_bf16 v[14:17], v[144:147], v[246:249], v[14:17]
	v_mfma_f32_16x16x32_bf16 v[6:9], v[164:167], v[246:249], v[6:9]
	s_setprio 0
	s_setprio 1
	v_mfma_f32_16x16x32_bf16 v[58:61], v[168:171], v[198:201], v[58:61]
	v_mfma_f32_16x16x32_bf16 v[50:53], v[176:179], v[198:201], v[50:53]
	v_mfma_f32_16x16x32_bf16 v[42:45], v[168:171], v[206:209], v[42:45]
	v_mfma_f32_16x16x32_bf16 v[34:37], v[176:179], v[206:209], v[34:37]
	v_mfma_f32_16x16x32_bf16 v[26:29], v[168:171], v[234:237], v[26:29]
	v_mfma_f32_16x16x32_bf16 v[18:21], v[176:179], v[234:237], v[18:21]
	v_mfma_f32_16x16x32_bf16 v[10:13], v[168:171], v[242:245], v[10:13]
	v_mfma_f32_16x16x32_bf16 v[2:5], v[176:179], v[242:245], v[2:5]
	v_mfma_f32_16x16x32_bf16 v[58:61], v[172:175], v[202:205], v[58:61]
	v_mfma_f32_16x16x32_bf16 v[50:53], v[194:197], v[202:205], v[50:53]
	v_mfma_f32_16x16x32_bf16 v[42:45], v[172:175], v[210:213], v[42:45]
	v_mfma_f32_16x16x32_bf16 v[34:37], v[194:197], v[210:213], v[34:37]
	v_mfma_f32_16x16x32_bf16 v[26:29], v[172:175], v[238:241], v[26:29]
	v_mfma_f32_16x16x32_bf16 v[18:21], v[194:197], v[238:241], v[18:21]
	v_mfma_f32_16x16x32_bf16 v[10:13], v[172:175], v[246:249], v[10:13]
	v_mfma_f32_16x16x32_bf16 v[2:5], v[194:197], v[246:249], v[2:5]
	s_setprio 0
	s_barrier
; #define PG8_STAGE(bufoff, gbase, voff) do { _Pragma("unroll") for (int _i = 0; _i < 2; ++_i) \
;         __builtin_amdgcn_global_load_lds((const unsigned*)((const char*)(gbase) + (voff)[_i]), (LAS unsigned*)(lds + (bufoff) + ldsw + _i * 8192), 16, 0, 0); } while (0)
; #define PG8_LDA(dst, b, h) do { _Pragma("unroll") for (int m = 0; m < 4; ++m) _Pragma("unroll") for (int k = 0; k < 2; ++k) dst[m][k] = *(const LAS bf16x8*)(lds + PG8_SA(b, h) + aoff + m * 2048 + k * 1024); } while (0)
; #define PG8_LDB(dst, b, h) do { _Pragma("unroll") for (int n = 0; n < 2; ++n) _Pragma("unroll") for (int k = 0; k < 2; ++k) dst[n][k] = *(const LAS bf16x8*)(lds + PG8_SB(b, h) + boff + n * 2048 + k * 1024); } while (0)
; #define PG8_MMA(ai, bj, At, Bt) do { __builtin_amdgcn_s_setprio(1); _Pragma("unroll") for (int m = 0; m < 4; ++m) _Pragma("unroll") for (int n = 0; n < 2; ++n) _Pragma("unroll") for (int k = 0; k < 2; ++k) \
;         acc[ai][bj][m][n] = __builtin_amdgcn_mfma_f32_16x16x32_bf16(Bt[n][k], At[m][k], acc[ai][bj][m][n], 0, 0, 0); __builtin_amdgcn_s_setprio(0); } while (0)
; #define PG8_WAIT_V(n) asm volatile("s_waitcnt vmcnt(" #n ")" ::: "memory")
; #define PG8_WAIT_L(n) asm volatile("s_waitcnt lgkmcnt(" #n ")" ::: "memory")
; #define PG8_BAR __builtin_amdgcn_s_barrier()
; #define PG8_SCHED __builtin_amdgcn_sched_barrier(0)
; template <class Epi, class Sched, bool ALIGN_EPI = true, bool SP2 = true>
; __device__ __forceinline__ void gemm_phase(LAS unsigned char* lds, const Gemm g, const Sched& S, const Epi& E) {
;     ...
;             PG8_LDB(B0, 1, 0); PG8_LDB(B1, 1, 1); PG8_SCHED; PG8_LDA(At, 1, 0); PG8_STAGE(PG8_SA(0, 1), a2 + hstep, voffA);
;             PG8_WAIT_V(8); PG8_WAIT_L(0); PG8_BAR; PG8_MMA(0, 0, At, B0); PG8_MMA(0, 1, At, B1); PG8_BAR; PG8_SCHED;
;             PG8_LDA(At, 1, 1); PG8_STAGE(PG8_SB(1, 0), b3, voffB); PG8_STAGE(PG8_SB(1, 1), b3 + hstep, voffB); PG8_STAGE(PG8_SA(1, 0), a3, voffA);
;             PG8_WAIT_V(8); PG8_WAIT_L(0); PG8_BAR; PG8_MMA(1, 0, At, B0); PG8_MMA(1, 1, At, B1); PG8_BAR; PG8_SCHED;
	s_add_i32 s58, 0, 0x18000
	v_add_u32_e32 v150, s58, v153
	s_add_i32 s59, 0, 0x1c000
	ds_read_b128 v[140:143], v150
	ds_read_b128 v[144:147], v150 offset:1024
	ds_read_b128 v[160:163], v150 offset:2048
	ds_read_b128 v[164:167], v150 offset:3072
	ds_read_b128 v[168:171], v150 offset:16384
	ds_read_b128 v[172:175], v150 offset:17408
	ds_read_b128 v[176:179], v150 offset:18432
	ds_read_b128 v[194:197], v150 offset:19456
	s_add_u32 s22, s22, 0x80000
	s_addc_u32 s23, s23, 0
	s_mov_b32 m0, s29
	ds_read_b128 v[198:201], v159 offset:32768
	ds_read_b128 v[202:205], v159 offset:33792
	ds_read_b128 v[206:209], v159 offset:34816
	ds_read_b128 v[210:213], v159 offset:35840
	ds_read_b128 v[234:237], v159 offset:36864
	ds_read_b128 v[238:241], v159 offset:37888
	ds_read_b128 v[242:245], v159 offset:38912
	ds_read_b128 v[246:249], v159 offset:39936
	global_load_lds_dwordx4 v134, s[22:23]
	s_mov_b32 m0, s30
	s_nop 0
	global_load_lds_dwordx4 v132, s[22:23]
	s_nop 0
	s_nop 0
	s_nop 0
	s_nop 0
	s_nop 0
	s_nop 0
	s_waitcnt vmcnt(8)
	s_waitcnt lgkmcnt(0)
	s_barrier
	s_setprio 1
	s_waitcnt lgkmcnt(0)
	v_mfma_f32_16x16x32_bf16 v[126:129], v[140:143], v[198:201], v[126:129]
	v_mfma_f32_16x16x32_bf16 v[118:121], v[160:163], v[198:201], v[118:121]
	v_mfma_f32_16x16x32_bf16 v[110:113], v[140:143], v[206:209], v[110:113]
	v_mfma_f32_16x16x32_bf16 v[102:105], v[160:163], v[206:209], v[102:105]
	v_mfma_f32_16x16x32_bf16 v[94:97], v[140:143], v[234:237], v[94:97]
	v_mfma_f32_16x16x32_bf16 v[86:89], v[160:163], v[234:237], v[86:89]
	v_mfma_f32_16x16x32_bf16 v[78:81], v[140:143], v[242:245], v[78:81]
	v_mfma_f32_16x16x32_bf16 v[70:73], v[160:163], v[242:245], v[70:73]
	v_mfma_f32_16x16x32_bf16 v[126:129], v[144:147], v[202:205], v[126:129]
	v_mfma_f32_16x16x32_bf16 v[118:121], v[164:167], v[202:205], v[118:121]
	v_mfma_f32_16x16x32_bf16 v[110:113], v[144:147], v[210:213], v[110:113]
	v_mfma_f32_16x16x32_bf16 v[102:105], v[164:167], v[210:213], v[102:105]
	v_mfma_f32_16x16x32_bf16 v[94:97], v[144:147], v[238:241], v[94:97]
	v_mfma_f32_16x16x32_bf16 v[86:89], v[164:167], v[238:241], v[86:89]
	v_mfma_f32_16x16x32_bf16 v[78:81], v[144:147], v[246:249], v[78:81]
	v_mfma_f32_16x16x32_bf16 v[70:73], v[164:167], v[246:249], v[70:73]
	s_setprio 0
	s_setprio 1
	v_mfma_f32_16x16x32_bf16 v[122:125], v[168:171], v[198:201], v[122:125]
	v_mfma_f32_16x16x32_bf16 v[114:117], v[176:179], v[198:201], v[114:117]
	v_mfma_f32_16x16x32_bf16 v[106:109], v[168:171], v[206:209], v[106:109]
	v_mfma_f32_16x16x32_bf16 v[98:101], v[176:179], v[206:209], v[98:101]
	v_mfma_f32_16x16x32_bf16 v[90:93], v[168:171], v[234:237], v[90:93]
	v_mfma_f32_16x16x32_bf16 v[82:85], v[176:179], v[234:237], v[82:85]
	v_mfma_f32_16x16x32_bf16 v[74:77], v[168:171], v[242:245], v[74:77]
	v_mfma_f32_16x16x32_bf16 v[66:69], v[176:179], v[242:245], v[66:69]
	v_mfma_f32_16x16x32_bf16 v[122:125], v[172:175], v[202:205], v[122:125]
	v_mfma_f32_16x16x32_bf16 v[114:117], v[194:197], v[202:205], v[114:117]
	v_mfma_f32_16x16x32_bf16 v[106:109], v[172:175], v[210:213], v[106:109]
	v_mfma_f32_16x16x32_bf16 v[98:101], v[194:197], v[210:213], v[98:101]
	v_mfma_f32_16x16x32_bf16 v[90:93], v[172:175], v[238:241], v[90:93]
	v_mfma_f32_16x16x32_bf16 v[82:85], v[194:197], v[238:241], v[82:85]
	v_mfma_f32_16x16x32_bf16 v[74:77], v[172:175], v[246:249], v[74:77]
	v_mfma_f32_16x16x32_bf16 v[66:69], v[194:197], v[246:249], v[66:69]
	s_setprio 0
	s_barrier
	s_add_i32 s32, s58, s26
	s_add_u32 s6, s6, s92
	s_addc_u32 s7, s7, s93
	s_mov_b32 m0, s32
	ds_read_b128 v[198:201], v159 offset:49152
	ds_read_b128 v[202:205], v159 offset:50176
	ds_read_b128 v[206:209], v159 offset:51200
	ds_read_b128 v[210:213], v159 offset:52224
	ds_read_b128 v[234:237], v159 offset:53248
	ds_read_b128 v[238:241], v159 offset:54272
	ds_read_b128 v[242:245], v159 offset:55296
	ds_read_b128 v[246:249], v159 offset:56320
	global_load_lds_dwordx4 v0, s[6:7]
	s_add_i32 m0, s32, 0x2000
	s_add_i32 s32, s59, s26
	global_load_lds_dwordx4 v130, s[6:7]
	s_add_u32 s6, s6, 0x80000
	s_addc_u32 s7, s7, 0
	s_mov_b32 m0, s32
	s_nop 0
	global_load_lds_dwordx4 v0, s[6:7]
	s_add_i32 m0, s32, 0x2000
	s_nop 0
	global_load_lds_dwordx4 v130, s[6:7]
	s_add_u32 s22, s22, 0xfff80080
	s_addc_u32 s23, s23, -1
	s_mov_b32 m0, s31
	s_nop 0
	global_load_lds_dwordx4 v134, s[22:23]
	s_mov_b32 m0, s34
	s_nop 0
	global_load_lds_dwordx4 v132, s[22:23]
	s_nop 0
	s_nop 0
	s_nop 0
	s_nop 0
	s_nop 0
	s_nop 0
	s_waitcnt vmcnt(8)
	s_waitcnt lgkmcnt(0)
	s_barrier
	s_setprio 1
	s_waitcnt lgkmcnt(0)
	v_mfma_f32_16x16x32_bf16 v[62:65], v[140:143], v[198:201], v[62:65]
	v_mfma_f32_16x16x32_bf16 v[54:57], v[160:163], v[198:201], v[54:57]
	v_mfma_f32_16x16x32_bf16 v[46:49], v[140:143], v[206:209], v[46:49]
	v_mfma_f32_16x16x32_bf16 v[38:41], v[160:163], v[206:209], v[38:41]
	v_mfma_f32_16x16x32_bf16 v[30:33], v[140:143], v[234:237], v[30:33]
	v_mfma_f32_16x16x32_bf16 v[22:25], v[160:163], v[234:237], v[22:25]
	v_mfma_f32_16x16x32_bf16 v[14:17], v[140:143], v[242:245], v[14:17]
	v_mfma_f32_16x16x32_bf16 v[6:9], v[160:163], v[242:245], v[6:9]
	v_mfma_f32_16x16x32_bf16 v[62:65], v[144:147], v[202:205], v[62:65]
	v_mfma_f32_16x16x32_bf16 v[54:57], v[164:167], v[202:205], v[54:57]
	v_mfma_f32_16x16x32_bf16 v[46:49], v[144:147], v[210:213], v[46:49]
	v_mfma_f32_16x16x32_bf16 v[38:41], v[164:167], v[210:213], v[38:41]
	v_mfma_f32_16x16x32_bf16 v[30:33], v[144:147], v[238:241], v[30:33]
	v_mfma_f32_16x16x32_bf16 v[22:25], v[164:167], v[238:241], v[22:25]
	v_mfma_f32_16x16x32_bf16 v[14:17], v[144:147], v[246:249], v[14:17]
	v_mfma_f32_16x16x32_bf16 v[6:9], v[164:167], v[246:249], v[6:9]
	s_setprio 0
	s_setprio 1
	v_mfma_f32_16x16x32_bf16 v[58:61], v[168:171], v[198:201], v[58:61]
	v_mfma_f32_16x16x32_bf16 v[50:53], v[176:179], v[198:201], v[50:53]
	v_mfma_f32_16x16x32_bf16 v[42:45], v[168:171], v[206:209], v[42:45]
	v_mfma_f32_16x16x32_bf16 v[34:37], v[176:179], v[206:209], v[34:37]
	v_mfma_f32_16x16x32_bf16 v[26:29], v[168:171], v[234:237], v[26:29]
	v_mfma_f32_16x16x32_bf16 v[18:21], v[176:179], v[234:237], v[18:21]
	v_mfma_f32_16x16x32_bf16 v[10:13], v[168:171], v[242:245], v[10:13]
	v_mfma_f32_16x16x32_bf16 v[2:5], v[176:179], v[242:245], v[2:5]
	v_mfma_f32_16x16x32_bf16 v[58:61], v[172:175], v[202:205], v[58:61]
	v_mfma_f32_16x16x32_bf16 v[50:53], v[194:197], v[202:205], v[50:53]
	v_mfma_f32_16x16x32_bf16 v[42:45], v[172:175], v[210:213], v[42:45]
	v_mfma_f32_16x16x32_bf16 v[34:37], v[194:197], v[210:213], v[34:37]
	v_mfma_f32_16x16x32_bf16 v[26:29], v[172:175], v[238:241], v[26:29]
	v_mfma_f32_16x16x32_bf16 v[18:21], v[194:197], v[238:241], v[18:21]
	v_mfma_f32_16x16x32_bf16 v[10:13], v[172:175], v[246:249], v[10:13]
	v_mfma_f32_16x16x32_bf16 v[2:5], v[194:197], v[246:249], v[2:5]
	s_setprio 0
	s_barrier
	s_add_i32 s74, s74, 2
	s_add_u32 s4, s4, 0x100
	s_addc_u32 s5, s5, 0
	s_add_u32 s72, s72, 0x100
	s_addc_u32 s73, s73, 0
	s_cmp_gt_u32 s74, 29
	s_cbranch_scc0 .LBB0_871
	s_and_b64 vcc, exec, s[12:13]
	s_cbranch_vccz .LBB0_874
	s_barrier
